# gl1 forget-gate projection on the matrix core: 4x v_mfma_f32_32x32x16_bf16 (K=16 low-rank width) + v_permlane32_swap to column-per-lane layout, replaces 512 dot2c per item
# baseline (speedup 1.0000x reference)
; __device__ __forceinline__ unsigned pk2(float lo, float hi) { unsigned r; asm("v_cvt_pk_bf16_f32 %0, %1, %2" : "=v"(r) : "v"(lo), "v"(hi)); return r; }
; __device__ __forceinline__ void gl1_item(PREF p, int l, int item, bool valid, LAS unsigned char* pl, int sw, int lane) {
;     ...
;     if (valid) {
;         const bf16_t* prl = P + (size_t)(row0 + lane * rstride) * PW + 2560 + d * 16;
;         const u32x4 lra = *(const u32x4*)prl, lrb = *(const u32x4*)(prl + 8);
;         unsigned lrp[8] = {lra.x, lra.y, lra.z, lra.w, lrb.x, lrb.y, lrb.z, lrb.w};
;         float qc[16], kc[16];
; #pragma unroll
;         for (int ss = 0; ss < 16; ++ss) { const int i = d ? 63 - ss : ss; const bf16_t* pr = P + (size_t)(row0 + i * rstride) * PW + h * 64 + lane;
;             qc[ss] = __builtin_bit_cast(float, (unsigned)pr[1024]); kc[ss] = __builtin_bit_cast(float, (unsigned)pr[1280]); }
;         __builtin_amdgcn_sched_barrier(0);
; #pragma unroll
;         for (int ss = 0; ss < 16; ++ss) { qc[ss] = bf2f(__builtin_bit_cast(unsigned, qc[ss])); kc[ss] = bf2f(__builtin_bit_cast(unsigned, kc[ss])); }
;         unsigned wupp[8];
; #pragma unroll
;         for (int r2 = 0; r2 < 8; ++r2) wupp[r2] = pk2(p.gla_wup[(size_t)((l * 2 + d) * 16 + 2 * r2) * 256 + h * 64 + lane], p.gla_wup[(size_t)((l * 2 + d) * 16 + 2 * r2 + 1) * 256 + h * 64 + lane]);
;         const float bup = p.gla_bup[(l * 2 + d) * 256 + h * 64 + lane];
; #pragma unroll 1
;         for (int g2 = 0; g2 < 2; ++g2) {
;             unsigned vr[16];
; #pragma unroll
;             for (int ii = 0; ii < 16; ++ii) { const int i = 32 * sw + g2 * 16 + ii; vr[ii] = *(const unsigned*)(P + (size_t)(row0 + i * rstride) * PW + 1536 + h * 128 + 2 * lane); }
; #pragma unroll
;             for (int ii = 0; ii < 16; ++ii) { const int i = 32 * sw + g2 * 16 + ii; sVt[(2 * lane) * 72 + i] = (bf16_t)(vr[ii] & 0xffffu); sVt[(2 * lane + 1) * 72 + i] = (bf16_t)(vr[ii] >> 16); }
.LBB0_188:
	s_cmpk_lt_i32 s0, 0x820
	s_cselect_b64 s[12:13], -1, 0
	s_and_b64 s[4:5], s[4:5], exec
	s_cselect_b32 s41, s3, s1
	s_cselect_b32 s1, s30, s2
	s_lshl_b32 s42, s1, 3
	s_cmpk_gt_i32 s0, 0x81f
	s_cbranch_scc1 .LBB0_199
	v_readlane_b32 s52, v253, 55
	v_readlane_b32 s53, v253, 56
	s_and_b32 s1, s0, 3
	s_nop 3
	s_load_dwordx2 s[2:3], s[52:53], 0xc0
	s_load_dwordx4 s[4:7], s[52:53], 0x90
	v_readlane_b32 s30, v254, 5
	v_readlane_b32 s45, v254, 11
	s_and_b32 s46, s38, 1
	v_lshlrev_b32_e32 v134, 1, v64
	v_lshlrev_b32_e32 v135, 2, v64
	s_lshr_b32 s47, s45, 7
	s_mul_i32 s47, s47, 0x9200
	s_lshl_b32 s48, s30, 1
	s_add_i32 s48, s48, s46
	s_waitcnt lgkmcnt(0)
	v_and_b32_e32 v87, 31, v64
	s_mul_i32 s50, s46, 63
	s_lshl_b32 s51, s46, 1
	s_sub_i32 s51, 1, s51
	v_lshrrev_b32_e32 v89, 5, v64
	v_lshlrev_b32_e32 v122, 2, v87
	v_lshl_add_u32 v123, v89, 13, v122
	v_mul_lo_u32 v87, v87, s51
	v_add_u32_e32 v87, s50, v87
	s_mul_i32 s51, s51, s44
	s_mul_i32 s51, s51, 0x2c000
	v_mul_lo_u32 v86, v87, s44
	v_add_u32_e32 v86, s43, v86
	s_mov_b32 s49, 0x1600
	s_lshl_b32 s50, s46, 5
	s_add_i32 s50, s50, 0x1400
	s_add_u32 s52, s2, 0xbc00000
	s_addc_u32 s53, s3, 0
	v_mul_lo_u32 v88, v86, s49
	v_add_u32_e32 v88, s50, v88
	v_lshl_add_u32 v88, v89, 4, v88
	global_load_dwordx4 v[0:3], v88, s[52:53]
	v_add_u32_e32 v88, s51, v88
	global_load_dwordx4 v[4:7], v88, s[52:53]
	s_lshl_b32 s50, s48, 14
	s_lshl_b32 s51, s1, 8
	s_add_i32 s50, s50, s51
	s_add_u32 s4, s4, s50
	s_addc_u32 s5, s5, 0
	global_load_dword v90, v123, s[4:5]
	global_load_dword v98, v123, s[4:5] offset:128
	global_load_dword v91, v123, s[4:5] offset:1024
	global_load_dword v99, v123, s[4:5] offset:1152
	global_load_dword v92, v123, s[4:5] offset:2048
	global_load_dword v100, v123, s[4:5] offset:2176
	global_load_dword v93, v123, s[4:5] offset:3072
	global_load_dword v101, v123, s[4:5] offset:3200
	s_add_u32 s4, s4, 0x1000
	s_addc_u32 s5, s5, 0
	global_load_dword v94, v123, s[4:5]
	global_load_dword v102, v123, s[4:5] offset:128
	global_load_dword v95, v123, s[4:5] offset:1024
	global_load_dword v103, v123, s[4:5] offset:1152
	global_load_dword v96, v123, s[4:5] offset:2048
	global_load_dword v104, v123, s[4:5] offset:2176
	global_load_dword v97, v123, s[4:5] offset:3072
	global_load_dword v105, v123, s[4:5] offset:3200
	s_lshl_b32 s50, s48, 10
	s_add_i32 s50, s50, s51
	s_add_u32 s6, s6, s50
	s_addc_u32 s7, s7, 0
	global_load_dword v16, v122, s[6:7]
	global_load_dword v124, v122, s[6:7] offset:128
	s_mul_i32 s54, s44, 0x1600
	s_lshl_b32 s50, s46, 5
	s_mul_i32 s50, s50, s44
	s_add_i32 s50, s50, s43
	s_mul_hi_u32 s7, s50, 0x1600
	s_mul_i32 s6, s50, 0x1600
	s_add_u32 s6, s6, s52
	s_addc_u32 s7, s7, s53
	s_add_i32 s51, s51, 0xc00
	s_add_u32 s6, s6, s51
	s_addc_u32 s7, s7, 0
	global_load_dword v34, v135, s[6:7]
	s_add_u32 s6, s6, s54
	s_addc_u32 s7, s7, 0
	global_load_dword v35, v135, s[6:7]
	s_add_u32 s6, s6, s54
	s_addc_u32 s7, s7, 0
	global_load_dword v36, v135, s[6:7]
	s_add_u32 s6, s6, s54
	s_addc_u32 s7, s7, 0
	global_load_dword v37, v135, s[6:7]
	s_add_u32 s6, s6, s54
	s_addc_u32 s7, s7, 0
	global_load_dword v38, v135, s[6:7]
	s_add_u32 s6, s6, s54
	s_addc_u32 s7, s7, 0
	global_load_dword v39, v135, s[6:7]
	s_add_u32 s6, s6, s54
	s_addc_u32 s7, s7, 0
	global_load_dword v40, v135, s[6:7]
	s_add_u32 s6, s6, s54
	s_addc_u32 s7, s7, 0
	global_load_dword v41, v135, s[6:7]
	s_add_u32 s6, s6, s54
	s_addc_u32 s7, s7, 0
	global_load_dword v42, v135, s[6:7]
	s_add_u32 s6, s6, s54
	s_addc_u32 s7, s7, 0
	global_load_dword v43, v135, s[6:7]
	s_add_u32 s6, s6, s54
	s_addc_u32 s7, s7, 0
	global_load_dword v44, v135, s[6:7]
	s_add_u32 s6, s6, s54
	s_addc_u32 s7, s7, 0
	global_load_dword v45, v135, s[6:7]
	s_add_u32 s6, s6, s54
	s_addc_u32 s7, s7, 0
	global_load_dword v46, v135, s[6:7]
	s_add_u32 s6, s6, s54
	s_addc_u32 s7, s7, 0
	global_load_dword v47, v135, s[6:7]
	s_add_u32 s6, s6, s54
	s_addc_u32 s7, s7, 0
	global_load_dword v212, v135, s[6:7]
	s_add_u32 s6, s6, s54
	s_addc_u32 s7, s7, 0
	global_load_dword v213, v135, s[6:7]
	s_add_u32 s6, s6, s54
	s_addc_u32 s7, s7, 0
	global_load_dword v214, v135, s[6:7]
	s_add_u32 s6, s6, s54
	s_addc_u32 s7, s7, 0
	global_load_dword v215, v135, s[6:7]
	s_add_u32 s6, s6, s54
	s_addc_u32 s7, s7, 0
	global_load_dword v216, v135, s[6:7]
	s_add_u32 s6, s6, s54
	s_addc_u32 s7, s7, 0
	global_load_dword v217, v135, s[6:7]
	s_add_u32 s6, s6, s54
	s_addc_u32 s7, s7, 0
	global_load_dword v218, v135, s[6:7]
	s_add_u32 s6, s6, s54
	s_addc_u32 s7, s7, 0
	global_load_dword v219, v135, s[6:7]
	s_add_u32 s6, s6, s54
	s_addc_u32 s7, s7, 0
	global_load_dword v222, v135, s[6:7]
	s_add_u32 s6, s6, s54
	s_addc_u32 s7, s7, 0
	global_load_dword v223, v135, s[6:7]
	s_add_u32 s6, s6, s54
	s_addc_u32 s7, s7, 0
	global_load_dword v228, v135, s[6:7]
	s_add_u32 s6, s6, s54
	s_addc_u32 s7, s7, 0
	global_load_dword v229, v135, s[6:7]
	s_add_u32 s6, s6, s54
	s_addc_u32 s7, s7, 0
	global_load_dword v230, v135, s[6:7]
	s_add_u32 s6, s6, s54
	s_addc_u32 s7, s7, 0
	global_load_dword v231, v135, s[6:7]
	s_add_u32 s6, s6, s54
	s_addc_u32 s7, s7, 0
	global_load_dword v232, v135, s[6:7]
	s_add_u32 s6, s6, s54
	s_addc_u32 s7, s7, 0
	global_load_dword v233, v135, s[6:7]
	s_add_u32 s6, s6, s54
	s_addc_u32 s7, s7, 0
	global_load_dword v234, v135, s[6:7]
	s_add_u32 s6, s6, s54
	s_addc_u32 s7, s7, 0
	global_load_dword v235, v135, s[6:7]
	s_mul_i32 s50, s46, 63
	s_mov_b32 s30, s50
	s_mul_i32 s50, s50, s44
	s_add_i32 s50, s50, s43
	s_mul_hi_u32 s7, s50, 0x1600
	s_mul_i32 s6, s50, 0x1600
	s_add_u32 s6, s6, s52
	s_addc_u32 s7, s7, s53
	s_lshl_b32 s51, s1, 7
	s_add_i32 s45, s51, 0x800
	s_add_u32 s6, s6, s45
	s_addc_u32 s7, s7, 0
	s_lshl_b32 s45, s50, 11
	s_add_u32 s4, s2, 0x16f00000
	s_addc_u32 s5, s3, 0
	s_add_u32 s4, s4, s45
	s_addc_u32 s5, s5, 0
	s_lshl_b32 s45, s46, 10
	s_add_i32 s45, s45, s51
	s_add_u32 s4, s4, s45
	s_addc_u32 s5, s5, 0
	s_lshl_b32 s56, s44, 11
	s_mov_b32 s55, 0
	s_mov_b32 s3, 0
	s_mov_b32 s2, 1
	s_cmp_eq_u32 s46, 0
	s_cbranch_scc1 .Lgl1v_fwd
	s_sub_u32 s54, 0, s54
	s_subb_u32 s55, 0, 0
	s_sub_u32 s56, 0, s56
	s_subb_u32 s3, 0, 0
	s_mov_b32 s2, -1
; __device__ __forceinline__ unsigned pk2(float lo, float hi) { unsigned r; asm("v_cvt_pk_bf16_f32 %0, %1, %2" : "=v"(r) : "v"(lo), "v"(hi)); return r; }
; __device__ __forceinline__ void gl1_item(PREF p, int l, int item, bool valid, LAS unsigned char* pl, int sw, int lane) {
;     ...
;         for (int ss = 0; ss < 16; ++ss) { const int i = d ? 63 - ss : ss; const bf16_t* pr = P + (size_t)(row0 + i * rstride) * PW + h * 64 + lane;
;             qc[ss] = __builtin_bit_cast(float, (unsigned)pr[1024]); kc[ss] = __builtin_bit_cast(float, (unsigned)pr[1280]); }
;         __builtin_amdgcn_sched_barrier(0);
; #pragma unroll
;         for (int ss = 0; ss < 16; ++ss) { qc[ss] = bf2f(__builtin_bit_cast(unsigned, qc[ss])); kc[ss] = bf2f(__builtin_bit_cast(unsigned, kc[ss])); }
;         unsigned wupp[8];
; #pragma unroll
;         for (int r2 = 0; r2 < 8; ++r2) wupp[r2] = pk2(p.gla_wup[(size_t)((l * 2 + d) * 16 + 2 * r2) * 256 + h * 64 + lane], p.gla_wup[(size_t)((l * 2 + d) * 16 + 2 * r2 + 1) * 256 + h * 64 + lane]);
;         const float bup = p.gla_bup[(l * 2 + d) * 256 + h * 64 + lane];
; #pragma unroll 1
;         for (int g2 = 0; g2 < 2; ++g2) {
;             unsigned vr[16];
; #pragma unroll
;             for (int ii = 0; ii < 16; ++ii) { const int i = 32 * sw + g2 * 16 + ii; vr[ii] = *(const unsigned*)(P + (size_t)(row0 + i * rstride) * PW + 1536 + h * 128 + 2 * lane); }
; #pragma unroll
;             for (int ii = 0; ii < 16; ++ii) { const int i = 32 * sw + g2 * 16 + ii; sVt[(2 * lane) * 72 + i] = (bf16_t)(vr[ii] & 0xffffu); sVt[(2 * lane + 1) * 72 + i] = (bf16_t)(vr[ii] >> 16); }
.Lgl1v_fwd:
	s_mul_i32 s45, s46, 0x2400
	s_add_i32 s45, s45, s47
	s_add_i32 s45, s45, 0x4800
	s_lshl_b32 s50, s30, 1
	s_add_i32 s45, s45, s50
	s_movk_i32 s50, 0x90
	v_mul_u32_u24_e32 v60, 0x90, v64
	v_add_u32_e32 v60, s45, v60
	s_lshl_b32 s50, s2, 1
	v_mov_b32_e32 v61, s50
	s_waitcnt vmcnt(32)
	v_cvt_pk_bf16_f32 v8, v90, v91
	v_cvt_pk_bf16_f32 v9, v92, v93
	v_cvt_pk_bf16_f32 v10, v94, v95
	v_cvt_pk_bf16_f32 v11, v96, v97
	v_cvt_pk_bf16_f32 v12, v98, v99
	v_cvt_pk_bf16_f32 v13, v100, v101
	v_cvt_pk_bf16_f32 v14, v102, v103
	v_cvt_pk_bf16_f32 v15, v104, v105
	s_waitcnt vmcnt(0)
	v_mul_u32_u24_e32 v86, 0x120, v64
	s_lshl_b32 s45, s46, 6
	s_add_i32 s45, s45, s47
	v_add_u32_e32 v86, s45, v86
	ds_write_b16 v86, v34 offset:0
	ds_write_b16_d16_hi v86, v34 offset:144
	ds_write_b16 v86, v35 offset:2
	ds_write_b16_d16_hi v86, v35 offset:146
	ds_write_b16 v86, v36 offset:4
	ds_write_b16_d16_hi v86, v36 offset:148
	ds_write_b16 v86, v37 offset:6
	ds_write_b16_d16_hi v86, v37 offset:150
	ds_write_b16 v86, v38 offset:8
	ds_write_b16_d16_hi v86, v38 offset:152
	ds_write_b16 v86, v39 offset:10
	ds_write_b16_d16_hi v86, v39 offset:154
	ds_write_b16 v86, v40 offset:12
	ds_write_b16_d16_hi v86, v40 offset:156
	ds_write_b16 v86, v41 offset:14
	ds_write_b16_d16_hi v86, v41 offset:158
	ds_write_b16 v86, v42 offset:16
	ds_write_b16_d16_hi v86, v42 offset:160
	ds_write_b16 v86, v43 offset:18
	ds_write_b16_d16_hi v86, v43 offset:162
	ds_write_b16 v86, v44 offset:20
	ds_write_b16_d16_hi v86, v44 offset:164
	ds_write_b16 v86, v45 offset:22
	ds_write_b16_d16_hi v86, v45 offset:166
	ds_write_b16 v86, v46 offset:24
	ds_write_b16_d16_hi v86, v46 offset:168
	ds_write_b16 v86, v47 offset:26
	ds_write_b16_d16_hi v86, v47 offset:170
	ds_write_b16 v86, v212 offset:28
	ds_write_b16_d16_hi v86, v212 offset:172
	ds_write_b16 v86, v213 offset:30
	ds_write_b16_d16_hi v86, v213 offset:174
	ds_write_b16 v86, v214 offset:32
	ds_write_b16_d16_hi v86, v214 offset:176
	ds_write_b16 v86, v215 offset:34
	ds_write_b16_d16_hi v86, v215 offset:178
	ds_write_b16 v86, v216 offset:36
	ds_write_b16_d16_hi v86, v216 offset:180
	ds_write_b16 v86, v217 offset:38
	ds_write_b16_d16_hi v86, v217 offset:182
	ds_write_b16 v86, v218 offset:40
	ds_write_b16_d16_hi v86, v218 offset:184
	ds_write_b16 v86, v219 offset:42
	ds_write_b16_d16_hi v86, v219 offset:186
	ds_write_b16 v86, v222 offset:44
	ds_write_b16_d16_hi v86, v222 offset:188
	ds_write_b16 v86, v223 offset:46
	ds_write_b16_d16_hi v86, v223 offset:190
	ds_write_b16 v86, v228 offset:48
	ds_write_b16_d16_hi v86, v228 offset:192
	ds_write_b16 v86, v229 offset:50
	ds_write_b16_d16_hi v86, v229 offset:194
	ds_write_b16 v86, v230 offset:52
	ds_write_b16_d16_hi v86, v230 offset:196
	ds_write_b16 v86, v231 offset:54
	ds_write_b16_d16_hi v86, v231 offset:198
	ds_write_b16 v86, v232 offset:56
	ds_write_b16_d16_hi v86, v232 offset:200
	ds_write_b16 v86, v233 offset:58
	ds_write_b16_d16_hi v86, v233 offset:202
	ds_write_b16 v86, v234 offset:60
	ds_write_b16_d16_hi v86, v234 offset:204
	ds_write_b16 v86, v235 offset:62
	ds_write_b16_d16_hi v86, v235 offset:206
	global_load_ushort v148, v134, s[6:7]
	global_load_ushort v164, v134, s[6:7] offset:512
	s_add_u32 s6, s6, s54
	s_addc_u32 s7, s7, s55
	global_load_ushort v149, v134, s[6:7]
	global_load_ushort v165, v134, s[6:7] offset:512
	s_add_u32 s6, s6, s54
	s_addc_u32 s7, s7, s55
	global_load_ushort v150, v134, s[6:7]
	global_load_ushort v166, v134, s[6:7] offset:512
	s_add_u32 s6, s6, s54
	s_addc_u32 s7, s7, s55
	global_load_ushort v151, v134, s[6:7]
	global_load_ushort v167, v134, s[6:7] offset:512
	s_add_u32 s6, s6, s54
	s_addc_u32 s7, s7, s55
	global_load_ushort v152, v134, s[6:7]
	global_load_ushort v168, v134, s[6:7] offset:512
	s_add_u32 s6, s6, s54
	s_addc_u32 s7, s7, s55
	global_load_ushort v153, v134, s[6:7]
	global_load_ushort v169, v134, s[6:7] offset:512
	s_add_u32 s6, s6, s54
	s_addc_u32 s7, s7, s55
	global_load_ushort v154, v134, s[6:7]
	global_load_ushort v170, v134, s[6:7] offset:512
	s_add_u32 s6, s6, s54
	s_addc_u32 s7, s7, s55
	global_load_ushort v155, v134, s[6:7]
	global_load_ushort v171, v134, s[6:7] offset:512
	s_add_u32 s6, s6, s54
	s_addc_u32 s7, s7, s55
	global_load_ushort v156, v134, s[6:7]
	global_load_ushort v172, v134, s[6:7] offset:512
	s_add_u32 s6, s6, s54
	s_addc_u32 s7, s7, s55
	global_load_ushort v157, v134, s[6:7]
	global_load_ushort v173, v134, s[6:7] offset:512
	s_add_u32 s6, s6, s54
	s_addc_u32 s7, s7, s55
	global_load_ushort v158, v134, s[6:7]
	global_load_ushort v174, v134, s[6:7] offset:512
	s_add_u32 s6, s6, s54
	s_addc_u32 s7, s7, s55
	global_load_ushort v159, v134, s[6:7]
	global_load_ushort v175, v134, s[6:7] offset:512
	s_add_u32 s6, s6, s54
	s_addc_u32 s7, s7, s55
	global_load_ushort v160, v134, s[6:7]
	global_load_ushort v176, v134, s[6:7] offset:512
	s_add_u32 s6, s6, s54
	s_addc_u32 s7, s7, s55
	global_load_ushort v161, v134, s[6:7]
	global_load_ushort v177, v134, s[6:7] offset:512
	s_add_u32 s6, s6, s54
	s_addc_u32 s7, s7, s55
	global_load_ushort v162, v134, s[6:7]
	global_load_ushort v178, v134, s[6:7] offset:512
	s_add_u32 s6, s6, s54
	s_addc_u32 s7, s7, s55
	global_load_ushort v163, v134, s[6:7]
	global_load_ushort v179, v134, s[6:7] offset:512
	s_add_u32 s6, s6, s54
	s_addc_u32 s7, s7, s55
	v_mov_b32_e32 v17, 0
	s_mov_b32 s1, 0xbfb8aa3b
	s_mov_b32 s49, 0xbd800000
	v_mov_b32_e32 v236, v16
	v_mov_b32_e32 v106, v124
	v_mov_b32_e32 v237, v16
	v_mov_b32_e32 v107, v124
	v_mov_b32_e32 v238, v16
	v_mov_b32_e32 v108, v124
	v_mov_b32_e32 v239, v16
	v_mov_b32_e32 v109, v124
	v_mov_b32_e32 v240, v16
	v_mov_b32_e32 v110, v124
	v_mov_b32_e32 v241, v16
	v_mov_b32_e32 v111, v124
; __device__ __forceinline__ void gl1_item(PREF p, int l, int item, bool valid, LAS unsigned char* pl, int sw, int lane) {
;     ...
;             for (int ss = 0; ss < 16; ++ss) { const int s = g4 * 16 + ss; const int i = d ? 63 - s : s;
;                 float z = bup;
; #pragma unroll
;                 for (int r2 = 0; r2 < 8; ++r2) { const unsigned w = (unsigned)__builtin_amdgcn_readlane((int)lrp[r2], i);
;                     z = __builtin_amdgcn_fdot2_f32_bf16(__builtin_bit_cast(bf16x2_t, w), __builtin_bit_cast(bf16x2_t, wupp[r2]), z, false); }
;                 gv[ss] = -(fmaxf(-z, 0.f) + __logf(1.f + __expf(-fabsf(z)))) * (1.f / 16.f);
;                 __builtin_amdgcn_sched_barrier(0);
;             }
; #pragma unroll
;             for (int ss = 0; ss < 16; ++ss) { const int s = g4 * 16 + ss; const int i = d ? 63 - s : s; const size_t rowi = (size_t)(row0 + i * rstride);
;                 bc += gv[ss];
;                 const float en = __expf(-bc), ep = __expf(bc);
	v_mov_b32_e32 v242, v16
	v_mov_b32_e32 v112, v124
	v_mov_b32_e32 v243, v16
	v_mov_b32_e32 v113, v124
	v_mov_b32_e32 v244, v16
	v_mov_b32_e32 v114, v124
	v_mov_b32_e32 v245, v16
	v_mov_b32_e32 v115, v124
	v_mov_b32_e32 v246, v16
	v_mov_b32_e32 v116, v124
	v_mov_b32_e32 v247, v16
	v_mov_b32_e32 v117, v124
	v_mov_b32_e32 v248, v16
	v_mov_b32_e32 v118, v124
	v_mov_b32_e32 v249, v16
	v_mov_b32_e32 v119, v124
	v_mov_b32_e32 v250, v16
	v_mov_b32_e32 v120, v124
	v_mov_b32_e32 v251, v16
	v_mov_b32_e32 v121, v124
	s_nop 1
	v_mfma_f32_32x32x16_bf16 v[236:251], v[0:3], v[8:11], v[236:251]
	v_mfma_f32_32x32x16_bf16 v[106:121], v[0:3], v[12:15], v[106:121]
	s_nop 15
	s_nop 15
	v_permlane32_swap_b32 v236, v106
	v_permlane32_swap_b32 v237, v107
	v_permlane32_swap_b32 v238, v108
	v_permlane32_swap_b32 v239, v109
	v_permlane32_swap_b32 v240, v110
	v_permlane32_swap_b32 v241, v111
	v_permlane32_swap_b32 v242, v112
	v_permlane32_swap_b32 v243, v113
	v_permlane32_swap_b32 v244, v114
	v_permlane32_swap_b32 v245, v115
	v_permlane32_swap_b32 v246, v116
	v_permlane32_swap_b32 v247, v117
	v_permlane32_swap_b32 v248, v118
	v_permlane32_swap_b32 v249, v119
	v_permlane32_swap_b32 v250, v120
	v_permlane32_swap_b32 v251, v121
	v_mul_f32_e64 v18, |v236|, s1
	v_mul_f32_e64 v19, |v237|, s1
	v_mul_f32_e64 v20, |v238|, s1
	v_mul_f32_e64 v21, |v239|, s1
	v_mul_f32_e64 v22, |v106|, s1
	v_mul_f32_e64 v23, |v107|, s1
	v_mul_f32_e64 v24, |v108|, s1
	v_mul_f32_e64 v25, |v109|, s1
	v_mul_f32_e64 v26, |v240|, s1
	v_mul_f32_e64 v27, |v241|, s1
	v_mul_f32_e64 v28, |v242|, s1
	v_mul_f32_e64 v29, |v243|, s1
	v_mul_f32_e64 v30, |v110|, s1
	v_mul_f32_e64 v31, |v111|, s1
	v_mul_f32_e64 v32, |v112|, s1
	v_mul_f32_e64 v33, |v113|, s1
	v_exp_f32_e32 v18, v18
	v_exp_f32_e32 v19, v19
	v_exp_f32_e32 v20, v20
	v_exp_f32_e32 v21, v21
	v_exp_f32_e32 v22, v22
	v_exp_f32_e32 v23, v23
	v_exp_f32_e32 v24, v24
	v_exp_f32_e32 v25, v25
	v_exp_f32_e32 v26, v26
	v_exp_f32_e32 v27, v27
	v_exp_f32_e32 v28, v28
	v_exp_f32_e32 v29, v29
	v_exp_f32_e32 v30, v30
	v_exp_f32_e32 v31, v31
	v_exp_f32_e32 v32, v32
	v_exp_f32_e32 v33, v33
	v_max_f32_e64 v236, -v236, 0
	v_max_f32_e64 v237, -v237, 0
	v_max_f32_e64 v238, -v238, 0
	v_max_f32_e64 v239, -v239, 0
	v_max_f32_e64 v106, -v106, 0
	v_max_f32_e64 v107, -v107, 0
	v_max_f32_e64 v108, -v108, 0
	v_max_f32_e64 v109, -v109, 0
	v_max_f32_e64 v240, -v240, 0
	v_max_f32_e64 v241, -v241, 0
	v_max_f32_e64 v242, -v242, 0
	v_max_f32_e64 v243, -v243, 0
	v_max_f32_e64 v110, -v110, 0
	v_max_f32_e64 v111, -v111, 0
	v_max_f32_e64 v112, -v112, 0
	v_max_f32_e64 v113, -v113, 0
	v_add_f32_e32 v18, 1.0, v18
	v_add_f32_e32 v19, 1.0, v19
	v_add_f32_e32 v20, 1.0, v20
	v_add_f32_e32 v21, 1.0, v21
	v_add_f32_e32 v22, 1.0, v22
	v_add_f32_e32 v23, 1.0, v23
	v_add_f32_e32 v24, 1.0, v24
	v_add_f32_e32 v25, 1.0, v25
	v_add_f32_e32 v26, 1.0, v26
	v_add_f32_e32 v27, 1.0, v27
	v_add_f32_e32 v28, 1.0, v28
	v_add_f32_e32 v29, 1.0, v29
	v_add_f32_e32 v30, 1.0, v30
	v_add_f32_e32 v31, 1.0, v31
	v_add_f32_e32 v32, 1.0, v32
	v_add_f32_e32 v33, 1.0, v33
	v_log_f32_e32 v18, v18
	v_log_f32_e32 v19, v19
	v_log_f32_e32 v20, v20
	v_log_f32_e32 v21, v21
	v_log_f32_e32 v22, v22
	v_log_f32_e32 v23, v23
	v_log_f32_e32 v24, v24
	v_log_f32_e32 v25, v25
	v_log_f32_e32 v26, v26
	v_log_f32_e32 v27, v27
	v_log_f32_e32 v28, v28
	v_log_f32_e32 v29, v29
	v_log_f32_e32 v30, v30
	v_log_f32_e32 v31, v31
	v_log_f32_e32 v32, v32
	v_log_f32_e32 v33, v33
	v_fmac_f32_e32 v236, 0x3f317218, v18
	v_fmac_f32_e32 v237, 0x3f317218, v19
	v_fmac_f32_e32 v238, 0x3f317218, v20
	v_fmac_f32_e32 v239, 0x3f317218, v21
	v_fmac_f32_e32 v106, 0x3f317218, v22
	v_fmac_f32_e32 v107, 0x3f317218, v23
	v_fmac_f32_e32 v108, 0x3f317218, v24
	v_fmac_f32_e32 v109, 0x3f317218, v25
	v_fmac_f32_e32 v240, 0x3f317218, v26
	v_fmac_f32_e32 v241, 0x3f317218, v27
	v_fmac_f32_e32 v242, 0x3f317218, v28
	v_fmac_f32_e32 v243, 0x3f317218, v29
	v_fmac_f32_e32 v110, 0x3f317218, v30
	v_fmac_f32_e32 v111, 0x3f317218, v31
	v_fmac_f32_e32 v112, 0x3f317218, v32
	v_fmac_f32_e32 v113, 0x3f317218, v33
	v_fma_f32 v70, v236, s49, v17
	v_fma_f32 v71, v237, s49, v70
	v_fma_f32 v72, v238, s49, v71
	v_fma_f32 v73, v239, s49, v72
	v_fma_f32 v74, v106, s49, v73
	v_fma_f32 v75, v107, s49, v74
	v_fma_f32 v76, v108, s49, v75
	v_fma_f32 v77, v109, s49, v76
	v_fma_f32 v78, v240, s49, v77
	v_fma_f32 v79, v241, s49, v78
	v_fma_f32 v80, v242, s49, v79
	v_fma_f32 v81, v243, s49, v80
	v_fma_f32 v82, v110, s49, v81
	v_fma_f32 v83, v111, s49, v82
	v_fma_f32 v84, v112, s49, v83
	v_fma_f32 v85, v113, s49, v84
	v_mov_b32_e32 v17, v85
	s_waitcnt vmcnt(0)
; __device__ __forceinline__ unsigned f2bf(float f) { unsigned r; asm("v_cvt_pk_bf16_f32 %0, %1, %1" : "=v"(r) : "v"(f)); return r & 0xffffu; }
; __device__ __forceinline__ void gl1_item(PREF p, int l, int item, bool valid, LAS unsigned char* pl, int sw, int lane) {
;     ...
;             if (g4 < 3) {
; #pragma unroll
;                 for (int ss = 0; ss < 16; ++ss) { const int s = (g4 + 1) * 16 + ss; const int i = d ? 63 - s : s; const bf16_t* pr = P + (size_t)(row0 + i * rstride) * PW + h * 64 + lane;
;                     qn[ss] = __builtin_bit_cast(float, (unsigned)pr[1024]); kn[ss] = __builtin_bit_cast(float, (unsigned)pr[1280]); }
;                 __builtin_amdgcn_sched_barrier(0);
;             }
;     ...
;             for (int ss = 0; ss < 16; ++ss) { const int s = g4 * 16 + ss; const int i = d ? 63 - s : s; const size_t rowi = (size_t)(row0 + i * rstride);
;                 bc += gv[ss];
;                 const float en = __expf(-bc), ep = __expf(bc);
;                 const float kt = kc[ss] * en, qt = qc[ss] * 0.125f * ep;
;                 const unsigned ktb = f2bf(kt);
;                 sKt[lane * 72 + i] = (bf16_t)ktb;
;                 QK[rowi * 1024 + d * 512 + h * 64 + lane] = (bf16_t)f2bf(qt);
;                 QK[rowi * 1024 + d * 512 + 256 + h * 64 + lane] = (bf16_t)ktb;
;             }
; #pragma unroll
;             for (int ss = 0; ss < 16; ++ss) { qc[ss] = bf2f(__builtin_bit_cast(unsigned, qn[ss])); kc[ss] = bf2f(__builtin_bit_cast(unsigned, kn[ss])); }
	global_load_ushort v180, v134, s[6:7]
	global_load_ushort v196, v134, s[6:7] offset:512
	s_add_u32 s6, s6, s54
	s_addc_u32 s7, s7, s55
	global_load_ushort v181, v134, s[6:7]
	global_load_ushort v197, v134, s[6:7] offset:512
	s_add_u32 s6, s6, s54
	s_addc_u32 s7, s7, s55
	global_load_ushort v182, v134, s[6:7]
	global_load_ushort v198, v134, s[6:7] offset:512
	s_add_u32 s6, s6, s54
	s_addc_u32 s7, s7, s55
	global_load_ushort v183, v134, s[6:7]
	global_load_ushort v199, v134, s[6:7] offset:512
	s_add_u32 s6, s6, s54
	s_addc_u32 s7, s7, s55
	global_load_ushort v184, v134, s[6:7]
	global_load_ushort v200, v134, s[6:7] offset:512
	s_add_u32 s6, s6, s54
	s_addc_u32 s7, s7, s55
	global_load_ushort v185, v134, s[6:7]
	global_load_ushort v201, v134, s[6:7] offset:512
	s_add_u32 s6, s6, s54
	s_addc_u32 s7, s7, s55
	global_load_ushort v186, v134, s[6:7]
	global_load_ushort v202, v134, s[6:7] offset:512
	s_add_u32 s6, s6, s54
	s_addc_u32 s7, s7, s55
	global_load_ushort v187, v134, s[6:7]
	global_load_ushort v203, v134, s[6:7] offset:512
	s_add_u32 s6, s6, s54
	s_addc_u32 s7, s7, s55
	global_load_ushort v188, v134, s[6:7]
	global_load_ushort v204, v134, s[6:7] offset:512
	s_add_u32 s6, s6, s54
	s_addc_u32 s7, s7, s55
	global_load_ushort v189, v134, s[6:7]
	global_load_ushort v205, v134, s[6:7] offset:512
	s_add_u32 s6, s6, s54
	s_addc_u32 s7, s7, s55
	global_load_ushort v190, v134, s[6:7]
	global_load_ushort v206, v134, s[6:7] offset:512
	s_add_u32 s6, s6, s54
	s_addc_u32 s7, s7, s55
	global_load_ushort v191, v134, s[6:7]
	global_load_ushort v207, v134, s[6:7] offset:512
	s_add_u32 s6, s6, s54
	s_addc_u32 s7, s7, s55
	global_load_ushort v192, v134, s[6:7]
	global_load_ushort v208, v134, s[6:7] offset:512
	s_add_u32 s6, s6, s54
	s_addc_u32 s7, s7, s55
	global_load_ushort v193, v134, s[6:7]
	global_load_ushort v209, v134, s[6:7] offset:512
	s_add_u32 s6, s6, s54
	s_addc_u32 s7, s7, s55
	global_load_ushort v194, v134, s[6:7]
	global_load_ushort v210, v134, s[6:7] offset:512
	s_add_u32 s6, s6, s54
	s_addc_u32 s7, s7, s55
	global_load_ushort v195, v134, s[6:7]
	global_load_ushort v211, v134, s[6:7] offset:512
	s_add_u32 s6, s6, s54
	s_addc_u32 s7, s7, s55
	v_mul_f32_e32 v18, 0xbfb8aa3b, v70
	v_mul_f32_e32 v19, 0xbfb8aa3b, v71
	v_mul_f32_e32 v20, 0xbfb8aa3b, v72
	v_mul_f32_e32 v21, 0xbfb8aa3b, v73
	v_mul_f32_e32 v22, 0xbfb8aa3b, v74
	v_mul_f32_e32 v23, 0xbfb8aa3b, v75
	v_mul_f32_e32 v24, 0xbfb8aa3b, v76
	v_mul_f32_e32 v25, 0xbfb8aa3b, v77
	v_mul_f32_e32 v26, 0xbfb8aa3b, v78
	v_mul_f32_e32 v27, 0xbfb8aa3b, v79
	v_mul_f32_e32 v28, 0xbfb8aa3b, v80
	v_mul_f32_e32 v29, 0xbfb8aa3b, v81
	v_mul_f32_e32 v30, 0xbfb8aa3b, v82
	v_mul_f32_e32 v31, 0xbfb8aa3b, v83
	v_mul_f32_e32 v32, 0xbfb8aa3b, v84
	v_mul_f32_e32 v33, 0xbfb8aa3b, v85
	v_exp_f32_e64 v236, -v18
	v_exp_f32_e64 v237, -v19
	v_exp_f32_e64 v238, -v20
	v_exp_f32_e64 v239, -v21
	v_exp_f32_e64 v106, -v22
	v_exp_f32_e64 v107, -v23
	v_exp_f32_e64 v108, -v24
	v_exp_f32_e64 v109, -v25
	v_exp_f32_e64 v240, -v26
	v_exp_f32_e64 v241, -v27
	v_exp_f32_e64 v242, -v28
	v_exp_f32_e64 v243, -v29
	v_exp_f32_e64 v110, -v30
	v_exp_f32_e64 v111, -v31
	v_exp_f32_e64 v112, -v32
	v_exp_f32_e64 v113, -v33
	v_exp_f32_e32 v18, v18
	v_exp_f32_e32 v19, v19
	v_exp_f32_e32 v20, v20
	v_exp_f32_e32 v21, v21
	v_exp_f32_e32 v22, v22
	v_exp_f32_e32 v23, v23
	v_exp_f32_e32 v24, v24
	v_exp_f32_e32 v25, v25
	v_exp_f32_e32 v26, v26
	v_exp_f32_e32 v27, v27
	v_exp_f32_e32 v28, v28
	v_exp_f32_e32 v29, v29
	v_exp_f32_e32 v30, v30
	v_exp_f32_e32 v31, v31
	v_exp_f32_e32 v32, v32
	v_exp_f32_e32 v33, v33
	v_lshlrev_b32_e32 v164, 16, v164
	v_lshlrev_b32_e32 v165, 16, v165
	v_lshlrev_b32_e32 v166, 16, v166
	v_lshlrev_b32_e32 v167, 16, v167
	v_lshlrev_b32_e32 v168, 16, v168
	v_lshlrev_b32_e32 v169, 16, v169
	v_lshlrev_b32_e32 v170, 16, v170
	v_lshlrev_b32_e32 v171, 16, v171
	v_lshlrev_b32_e32 v172, 16, v172
	v_lshlrev_b32_e32 v173, 16, v173
	v_lshlrev_b32_e32 v174, 16, v174
	v_lshlrev_b32_e32 v175, 16, v175
	v_lshlrev_b32_e32 v176, 16, v176
	v_lshlrev_b32_e32 v177, 16, v177
	v_lshlrev_b32_e32 v178, 16, v178
	v_lshlrev_b32_e32 v179, 16, v179
	v_lshlrev_b32_e32 v148, 16, v148
	v_lshlrev_b32_e32 v149, 16, v149
	v_lshlrev_b32_e32 v150, 16, v150
	v_lshlrev_b32_e32 v151, 16, v151
	v_lshlrev_b32_e32 v152, 16, v152
	v_lshlrev_b32_e32 v153, 16, v153
	v_lshlrev_b32_e32 v154, 16, v154
	v_lshlrev_b32_e32 v155, 16, v155
	v_lshlrev_b32_e32 v156, 16, v156
	v_lshlrev_b32_e32 v157, 16, v157
	v_lshlrev_b32_e32 v158, 16, v158
	v_lshlrev_b32_e32 v159, 16, v159
	v_lshlrev_b32_e32 v160, 16, v160
	v_lshlrev_b32_e32 v161, 16, v161
	v_lshlrev_b32_e32 v162, 16, v162
	v_lshlrev_b32_e32 v163, 16, v163
	v_mul_f32_e32 v18, v18, v164
	v_mul_f32_e32 v19, v19, v165
	v_mul_f32_e32 v20, v20, v166
	v_mul_f32_e32 v21, v21, v167
	v_mul_f32_e32 v22, v22, v168
	v_mul_f32_e32 v23, v23, v169
	v_mul_f32_e32 v24, v24, v170
	v_mul_f32_e32 v25, v25, v171
	v_mul_f32_e32 v26, v26, v172
	v_mul_f32_e32 v27, v27, v173
	v_mul_f32_e32 v28, v28, v174
	v_mul_f32_e32 v29, v29, v175
	v_mul_f32_e32 v30, v30, v176
	v_mul_f32_e32 v31, v31, v177
	v_mul_f32_e32 v32, v32, v178
	v_mul_f32_e32 v33, v33, v179
	v_mul_f32_e32 v70, 0x3e000000, v148
	v_mul_f32_e32 v71, 0x3e000000, v149
	v_mul_f32_e32 v72, 0x3e000000, v150
	v_mul_f32_e32 v73, 0x3e000000, v151
	v_mul_f32_e32 v74, 0x3e000000, v152
	v_mul_f32_e32 v75, 0x3e000000, v153
	v_mul_f32_e32 v76, 0x3e000000, v154
	v_mul_f32_e32 v77, 0x3e000000, v155
	v_mul_f32_e32 v78, 0x3e000000, v156
	v_mul_f32_e32 v79, 0x3e000000, v157
	v_mul_f32_e32 v80, 0x3e000000, v158
	v_mul_f32_e32 v81, 0x3e000000, v159
	v_mul_f32_e32 v82, 0x3e000000, v160
	v_mul_f32_e32 v83, 0x3e000000, v161
; __device__ __forceinline__ unsigned f2bf(float f) { unsigned r; asm("v_cvt_pk_bf16_f32 %0, %1, %1" : "=v"(r) : "v"(f)); return r & 0xffffu; }
; __device__ __forceinline__ void gl1_item(PREF p, int l, int item, bool valid, LAS unsigned char* pl, int sw, int lane) {
;     ...
;             for (int ss = 0; ss < 16; ++ss) { const int s = g4 * 16 + ss; const int i = d ? 63 - s : s;
;                 float z = bup;
; #pragma unroll
;                 for (int r2 = 0; r2 < 8; ++r2) { const unsigned w = (unsigned)__builtin_amdgcn_readlane((int)lrp[r2], i);
;                     z = __builtin_amdgcn_fdot2_f32_bf16(__builtin_bit_cast(bf16x2_t, w), __builtin_bit_cast(bf16x2_t, wupp[r2]), z, false); }
;                 gv[ss] = -(fmaxf(-z, 0.f) + __logf(1.f + __expf(-fabsf(z)))) * (1.f / 16.f);
;     ...
;             for (int ss = 0; ss < 16; ++ss) { const int s = g4 * 16 + ss; const int i = d ? 63 - s : s; const size_t rowi = (size_t)(row0 + i * rstride);
;                 bc += gv[ss];
;                 const float en = __expf(-bc), ep = __expf(bc);
;                 const float kt = kc[ss] * en, qt = qc[ss] * 0.125f * ep;
;                 const unsigned ktb = f2bf(kt);
;                 sKt[lane * 72 + i] = (bf16_t)ktb;
;                 QK[rowi * 1024 + d * 512 + h * 64 + lane] = (bf16_t)f2bf(qt);
;                 QK[rowi * 1024 + d * 512 + 256 + h * 64 + lane] = (bf16_t)ktb;
;             }
	v_mul_f32_e32 v84, 0x3e000000, v162
	v_mul_f32_e32 v85, 0x3e000000, v163
	v_mul_f32_e32 v236, v70, v236
	v_mul_f32_e32 v237, v71, v237
	v_mul_f32_e32 v238, v72, v238
	v_mul_f32_e32 v239, v73, v239
	v_mul_f32_e32 v106, v74, v106
	v_mul_f32_e32 v107, v75, v107
	v_mul_f32_e32 v108, v76, v108
	v_mul_f32_e32 v109, v77, v109
	v_mul_f32_e32 v240, v78, v240
	v_mul_f32_e32 v241, v79, v241
	v_mul_f32_e32 v242, v80, v242
	v_mul_f32_e32 v243, v81, v243
	v_mul_f32_e32 v110, v82, v110
	v_mul_f32_e32 v111, v83, v111
	v_mul_f32_e32 v112, v84, v112
	v_mul_f32_e32 v113, v85, v113
	v_cvt_pk_bf16_f32 v18, v18, v236
	v_cvt_pk_bf16_f32 v19, v19, v237
	v_cvt_pk_bf16_f32 v20, v20, v238
	v_cvt_pk_bf16_f32 v21, v21, v239
	v_cvt_pk_bf16_f32 v22, v22, v106
	v_cvt_pk_bf16_f32 v23, v23, v107
	v_cvt_pk_bf16_f32 v24, v24, v108
	v_cvt_pk_bf16_f32 v25, v25, v109
	v_cvt_pk_bf16_f32 v26, v26, v240
	v_cvt_pk_bf16_f32 v27, v27, v241
	v_cvt_pk_bf16_f32 v28, v28, v242
	v_cvt_pk_bf16_f32 v29, v29, v243
	v_cvt_pk_bf16_f32 v30, v30, v110
	v_cvt_pk_bf16_f32 v31, v31, v111
	v_cvt_pk_bf16_f32 v32, v32, v112
	v_cvt_pk_bf16_f32 v33, v33, v113
	ds_write_b16 v60, v18
	v_add_u32_e32 v60, v61, v60
	global_store_short_d16_hi v134, v18, s[4:5]
	global_store_short v134, v18, s[4:5] offset:512
	s_add_u32 s4, s4, s56
	s_addc_u32 s5, s5, s3
	ds_write_b16 v60, v19
	v_add_u32_e32 v60, v61, v60
	global_store_short_d16_hi v134, v19, s[4:5]
	global_store_short v134, v19, s[4:5] offset:512
	s_add_u32 s4, s4, s56
	s_addc_u32 s5, s5, s3
	ds_write_b16 v60, v20
	v_add_u32_e32 v60, v61, v60
	global_store_short_d16_hi v134, v20, s[4:5]
	global_store_short v134, v20, s[4:5] offset:512
	s_add_u32 s4, s4, s56
	s_addc_u32 s5, s5, s3
	ds_write_b16 v60, v21
	v_add_u32_e32 v60, v61, v60
	global_store_short_d16_hi v134, v21, s[4:5]
	global_store_short v134, v21, s[4:5] offset:512
	s_add_u32 s4, s4, s56
	s_addc_u32 s5, s5, s3
	ds_write_b16 v60, v22
	v_add_u32_e32 v60, v61, v60
	global_store_short_d16_hi v134, v22, s[4:5]
	global_store_short v134, v22, s[4:5] offset:512
	s_add_u32 s4, s4, s56
	s_addc_u32 s5, s5, s3
	ds_write_b16 v60, v23
	v_add_u32_e32 v60, v61, v60
	global_store_short_d16_hi v134, v23, s[4:5]
	global_store_short v134, v23, s[4:5] offset:512
	s_add_u32 s4, s4, s56
	s_addc_u32 s5, s5, s3
	ds_write_b16 v60, v24
	v_add_u32_e32 v60, v61, v60
	global_store_short_d16_hi v134, v24, s[4:5]
	global_store_short v134, v24, s[4:5] offset:512
	s_add_u32 s4, s4, s56
	s_addc_u32 s5, s5, s3
	ds_write_b16 v60, v25
	v_add_u32_e32 v60, v61, v60
	global_store_short_d16_hi v134, v25, s[4:5]
	global_store_short v134, v25, s[4:5] offset:512
	s_add_u32 s4, s4, s56
	s_addc_u32 s5, s5, s3
	ds_write_b16 v60, v26
	v_add_u32_e32 v60, v61, v60
	global_store_short_d16_hi v134, v26, s[4:5]
	global_store_short v134, v26, s[4:5] offset:512
	s_add_u32 s4, s4, s56
	s_addc_u32 s5, s5, s3
	ds_write_b16 v60, v27
	v_add_u32_e32 v60, v61, v60
	global_store_short_d16_hi v134, v27, s[4:5]
	global_store_short v134, v27, s[4:5] offset:512
	s_add_u32 s4, s4, s56
	s_addc_u32 s5, s5, s3
	ds_write_b16 v60, v28
	v_add_u32_e32 v60, v61, v60
	global_store_short_d16_hi v134, v28, s[4:5]
	global_store_short v134, v28, s[4:5] offset:512
	s_add_u32 s4, s4, s56
	s_addc_u32 s5, s5, s3
	ds_write_b16 v60, v29
	v_add_u32_e32 v60, v61, v60
	global_store_short_d16_hi v134, v29, s[4:5]
	global_store_short v134, v29, s[4:5] offset:512
	s_add_u32 s4, s4, s56
	s_addc_u32 s5, s5, s3
	ds_write_b16 v60, v30
	v_add_u32_e32 v60, v61, v60
	global_store_short_d16_hi v134, v30, s[4:5]
	global_store_short v134, v30, s[4:5] offset:512
	s_add_u32 s4, s4, s56
	s_addc_u32 s5, s5, s3
	ds_write_b16 v60, v31
	v_add_u32_e32 v60, v61, v60
	global_store_short_d16_hi v134, v31, s[4:5]
	global_store_short v134, v31, s[4:5] offset:512
	s_add_u32 s4, s4, s56
	s_addc_u32 s5, s5, s3
	ds_write_b16 v60, v32
	v_add_u32_e32 v60, v61, v60
	global_store_short_d16_hi v134, v32, s[4:5]
	global_store_short v134, v32, s[4:5] offset:512
	s_add_u32 s4, s4, s56
	s_addc_u32 s5, s5, s3
	ds_write_b16 v60, v33
	v_add_u32_e32 v60, v61, v60
	global_store_short_d16_hi v134, v33, s[4:5]
	global_store_short v134, v33, s[4:5] offset:512
	s_add_u32 s4, s4, s56
	s_addc_u32 s5, s5, s3
	v_mul_f32_e64 v18, |v244|, s1
	v_mul_f32_e64 v19, |v245|, s1
	v_mul_f32_e64 v20, |v246|, s1
	v_mul_f32_e64 v21, |v247|, s1
	v_mul_f32_e64 v22, |v114|, s1
	v_mul_f32_e64 v23, |v115|, s1
	v_mul_f32_e64 v24, |v116|, s1
	v_mul_f32_e64 v25, |v117|, s1
	v_mul_f32_e64 v26, |v248|, s1
	v_mul_f32_e64 v27, |v249|, s1
	v_mul_f32_e64 v28, |v250|, s1
	v_mul_f32_e64 v29, |v251|, s1
	v_mul_f32_e64 v30, |v118|, s1
	v_mul_f32_e64 v31, |v119|, s1
	v_mul_f32_e64 v32, |v120|, s1
	v_mul_f32_e64 v33, |v121|, s1
	v_exp_f32_e32 v18, v18
	v_exp_f32_e32 v19, v19
	v_exp_f32_e32 v20, v20
	v_exp_f32_e32 v21, v21
	v_exp_f32_e32 v22, v22
	v_exp_f32_e32 v23, v23
	v_exp_f32_e32 v24, v24
	v_exp_f32_e32 v25, v25
	v_exp_f32_e32 v26, v26
	v_exp_f32_e32 v27, v27
	v_exp_f32_e32 v28, v28
	v_exp_f32_e32 v29, v29
	v_exp_f32_e32 v30, v30
	v_exp_f32_e32 v31, v31
	v_exp_f32_e32 v32, v32
	v_exp_f32_e32 v33, v33
	v_max_f32_e64 v244, -v244, 0
	v_max_f32_e64 v245, -v245, 0
	v_max_f32_e64 v246, -v246, 0
	v_max_f32_e64 v247, -v247, 0
	v_max_f32_e64 v114, -v114, 0
	v_max_f32_e64 v115, -v115, 0
	v_max_f32_e64 v116, -v116, 0
	v_max_f32_e64 v117, -v117, 0
	v_max_f32_e64 v248, -v248, 0
	v_max_f32_e64 v249, -v249, 0
	v_max_f32_e64 v250, -v250, 0
	v_max_f32_e64 v251, -v251, 0
	v_max_f32_e64 v118, -v118, 0
	v_max_f32_e64 v119, -v119, 0
	v_max_f32_e64 v120, -v120, 0
	v_max_f32_e64 v121, -v121, 0
	v_add_f32_e32 v18, 1.0, v18
	v_add_f32_e32 v19, 1.0, v19
	v_add_f32_e32 v20, 1.0, v20
; __device__ __forceinline__ unsigned f2bf(float f) { unsigned r; asm("v_cvt_pk_bf16_f32 %0, %1, %1" : "=v"(r) : "v"(f)); return r & 0xffffu; }
; __device__ __forceinline__ void gl1_item(PREF p, int l, int item, bool valid, LAS unsigned char* pl, int sw, int lane) {
;     ...
;             float gv[16];
; #pragma unroll
;             for (int ss = 0; ss < 16; ++ss) { const int s = g4 * 16 + ss; const int i = d ? 63 - s : s;
;                 float z = bup;
; #pragma unroll
;                 for (int r2 = 0; r2 < 8; ++r2) { const unsigned w = (unsigned)__builtin_amdgcn_readlane((int)lrp[r2], i);
;                     z = __builtin_amdgcn_fdot2_f32_bf16(__builtin_bit_cast(bf16x2_t, w), __builtin_bit_cast(bf16x2_t, wupp[r2]), z, false); }
;                 gv[ss] = -(fmaxf(-z, 0.f) + __logf(1.f + __expf(-fabsf(z)))) * (1.f / 16.f);
;                 __builtin_amdgcn_sched_barrier(0);
;             }
; #pragma unroll
;             for (int ss = 0; ss < 16; ++ss) { const int s = g4 * 16 + ss; const int i = d ? 63 - s : s; const size_t rowi = (size_t)(row0 + i * rstride);
;                 bc += gv[ss];
;                 const float en = __expf(-bc), ep = __expf(bc);
;                 const float kt = kc[ss] * en, qt = qc[ss] * 0.125f * ep;
;                 const unsigned ktb = f2bf(kt);
;                 sKt[lane * 72 + i] = (bf16_t)ktb;
;                 QK[rowi * 1024 + d * 512 + h * 64 + lane] = (bf16_t)f2bf(qt);
;                 QK[rowi * 1024 + d * 512 + 256 + h * 64 + lane] = (bf16_t)ktb;
;             }
; #pragma unroll
;             for (int ss = 0; ss < 16; ++ss) { qc[ss] = bf2f(__builtin_bit_cast(unsigned, qn[ss])); kc[ss] = bf2f(__builtin_bit_cast(unsigned, kn[ss])); }
	v_add_f32_e32 v21, 1.0, v21
	v_add_f32_e32 v22, 1.0, v22
	v_add_f32_e32 v23, 1.0, v23
	v_add_f32_e32 v24, 1.0, v24
	v_add_f32_e32 v25, 1.0, v25
	v_add_f32_e32 v26, 1.0, v26
	v_add_f32_e32 v27, 1.0, v27
	v_add_f32_e32 v28, 1.0, v28
	v_add_f32_e32 v29, 1.0, v29
	v_add_f32_e32 v30, 1.0, v30
	v_add_f32_e32 v31, 1.0, v31
	v_add_f32_e32 v32, 1.0, v32
	v_add_f32_e32 v33, 1.0, v33
	v_log_f32_e32 v18, v18
	v_log_f32_e32 v19, v19
	v_log_f32_e32 v20, v20
	v_log_f32_e32 v21, v21
	v_log_f32_e32 v22, v22
	v_log_f32_e32 v23, v23
	v_log_f32_e32 v24, v24
	v_log_f32_e32 v25, v25
	v_log_f32_e32 v26, v26
	v_log_f32_e32 v27, v27
	v_log_f32_e32 v28, v28
	v_log_f32_e32 v29, v29
	v_log_f32_e32 v30, v30
	v_log_f32_e32 v31, v31
	v_log_f32_e32 v32, v32
	v_log_f32_e32 v33, v33
	v_fmac_f32_e32 v244, 0x3f317218, v18
	v_fmac_f32_e32 v245, 0x3f317218, v19
	v_fmac_f32_e32 v246, 0x3f317218, v20
	v_fmac_f32_e32 v247, 0x3f317218, v21
	v_fmac_f32_e32 v114, 0x3f317218, v22
	v_fmac_f32_e32 v115, 0x3f317218, v23
	v_fmac_f32_e32 v116, 0x3f317218, v24
	v_fmac_f32_e32 v117, 0x3f317218, v25
	v_fmac_f32_e32 v248, 0x3f317218, v26
	v_fmac_f32_e32 v249, 0x3f317218, v27
	v_fmac_f32_e32 v250, 0x3f317218, v28
	v_fmac_f32_e32 v251, 0x3f317218, v29
	v_fmac_f32_e32 v118, 0x3f317218, v30
	v_fmac_f32_e32 v119, 0x3f317218, v31
	v_fmac_f32_e32 v120, 0x3f317218, v32
	v_fmac_f32_e32 v121, 0x3f317218, v33
	v_fma_f32 v70, v244, s49, v17
	v_fma_f32 v71, v245, s49, v70
	v_fma_f32 v72, v246, s49, v71
	v_fma_f32 v73, v247, s49, v72
	v_fma_f32 v74, v114, s49, v73
	v_fma_f32 v75, v115, s49, v74
	v_fma_f32 v76, v116, s49, v75
	v_fma_f32 v77, v117, s49, v76
	v_fma_f32 v78, v248, s49, v77
	v_fma_f32 v79, v249, s49, v78
	v_fma_f32 v80, v250, s49, v79
	v_fma_f32 v81, v251, s49, v80
	v_fma_f32 v82, v118, s49, v81
	v_fma_f32 v83, v119, s49, v82
	v_fma_f32 v84, v120, s49, v83
	v_fma_f32 v85, v121, s49, v84
	v_mov_b32_e32 v17, v85
	s_waitcnt vmcnt(32)
	global_load_short_d16_hi v148, v134, s[6:7]
	global_load_short_d16_hi v164, v134, s[6:7] offset:512
	s_add_u32 s6, s6, s54
	s_addc_u32 s7, s7, s55
	global_load_short_d16_hi v149, v134, s[6:7]
	global_load_short_d16_hi v165, v134, s[6:7] offset:512
	s_add_u32 s6, s6, s54
	s_addc_u32 s7, s7, s55
	global_load_short_d16_hi v150, v134, s[6:7]
	global_load_short_d16_hi v166, v134, s[6:7] offset:512
	s_add_u32 s6, s6, s54
	s_addc_u32 s7, s7, s55
	global_load_short_d16_hi v151, v134, s[6:7]
	global_load_short_d16_hi v167, v134, s[6:7] offset:512
	s_add_u32 s6, s6, s54
	s_addc_u32 s7, s7, s55
	global_load_short_d16_hi v152, v134, s[6:7]
	global_load_short_d16_hi v168, v134, s[6:7] offset:512
	s_add_u32 s6, s6, s54
	s_addc_u32 s7, s7, s55
	global_load_short_d16_hi v153, v134, s[6:7]
	global_load_short_d16_hi v169, v134, s[6:7] offset:512
	s_add_u32 s6, s6, s54
	s_addc_u32 s7, s7, s55
	global_load_short_d16_hi v154, v134, s[6:7]
	global_load_short_d16_hi v170, v134, s[6:7] offset:512
	s_add_u32 s6, s6, s54
	s_addc_u32 s7, s7, s55
	global_load_short_d16_hi v155, v134, s[6:7]
	global_load_short_d16_hi v171, v134, s[6:7] offset:512
	s_add_u32 s6, s6, s54
	s_addc_u32 s7, s7, s55
	global_load_short_d16_hi v156, v134, s[6:7]
	global_load_short_d16_hi v172, v134, s[6:7] offset:512
	s_add_u32 s6, s6, s54
	s_addc_u32 s7, s7, s55
	global_load_short_d16_hi v157, v134, s[6:7]
	global_load_short_d16_hi v173, v134, s[6:7] offset:512
	s_add_u32 s6, s6, s54
	s_addc_u32 s7, s7, s55
	global_load_short_d16_hi v158, v134, s[6:7]
	global_load_short_d16_hi v174, v134, s[6:7] offset:512
	s_add_u32 s6, s6, s54
	s_addc_u32 s7, s7, s55
	global_load_short_d16_hi v159, v134, s[6:7]
	global_load_short_d16_hi v175, v134, s[6:7] offset:512
	s_add_u32 s6, s6, s54
	s_addc_u32 s7, s7, s55
	global_load_short_d16_hi v160, v134, s[6:7]
	global_load_short_d16_hi v176, v134, s[6:7] offset:512
	s_add_u32 s6, s6, s54
	s_addc_u32 s7, s7, s55
	global_load_short_d16_hi v161, v134, s[6:7]
	global_load_short_d16_hi v177, v134, s[6:7] offset:512
	s_add_u32 s6, s6, s54
	s_addc_u32 s7, s7, s55
	global_load_short_d16_hi v162, v134, s[6:7]
	global_load_short_d16_hi v178, v134, s[6:7] offset:512
	s_add_u32 s6, s6, s54
	s_addc_u32 s7, s7, s55
	global_load_short_d16_hi v163, v134, s[6:7]
	global_load_short_d16_hi v179, v134, s[6:7] offset:512
	s_add_u32 s6, s6, s54
	s_addc_u32 s7, s7, s55
	v_mul_f32_e32 v18, 0xbfb8aa3b, v70
	v_mul_f32_e32 v19, 0xbfb8aa3b, v71
	v_mul_f32_e32 v20, 0xbfb8aa3b, v72
	v_mul_f32_e32 v21, 0xbfb8aa3b, v73
	v_mul_f32_e32 v22, 0xbfb8aa3b, v74
	v_mul_f32_e32 v23, 0xbfb8aa3b, v75
	v_mul_f32_e32 v24, 0xbfb8aa3b, v76
	v_mul_f32_e32 v25, 0xbfb8aa3b, v77
	v_mul_f32_e32 v26, 0xbfb8aa3b, v78
	v_mul_f32_e32 v27, 0xbfb8aa3b, v79
	v_mul_f32_e32 v28, 0xbfb8aa3b, v80
	v_mul_f32_e32 v29, 0xbfb8aa3b, v81
	v_mul_f32_e32 v30, 0xbfb8aa3b, v82
	v_mul_f32_e32 v31, 0xbfb8aa3b, v83
	v_mul_f32_e32 v32, 0xbfb8aa3b, v84
	v_mul_f32_e32 v33, 0xbfb8aa3b, v85
	v_exp_f32_e64 v244, -v18
	v_exp_f32_e64 v245, -v19
	v_exp_f32_e64 v246, -v20
	v_exp_f32_e64 v247, -v21
	v_exp_f32_e64 v114, -v22
	v_exp_f32_e64 v115, -v23
	v_exp_f32_e64 v116, -v24
	v_exp_f32_e64 v117, -v25
	v_exp_f32_e64 v248, -v26
	v_exp_f32_e64 v249, -v27
	v_exp_f32_e64 v250, -v28
	v_exp_f32_e64 v251, -v29
	v_exp_f32_e64 v118, -v30
	v_exp_f32_e64 v119, -v31
	v_exp_f32_e64 v120, -v32
	v_exp_f32_e64 v121, -v33
	v_exp_f32_e32 v18, v18
	v_exp_f32_e32 v19, v19
	v_exp_f32_e32 v20, v20
	v_exp_f32_e32 v21, v21
	v_exp_f32_e32 v22, v22
	v_exp_f32_e32 v23, v23
	v_exp_f32_e32 v24, v24
	v_exp_f32_e32 v25, v25
	v_exp_f32_e32 v26, v26
	v_exp_f32_e32 v27, v27
	v_exp_f32_e32 v28, v28
	v_exp_f32_e32 v29, v29
	v_exp_f32_e32 v30, v30
	v_exp_f32_e32 v31, v31
	v_exp_f32_e32 v32, v32
; __device__ __forceinline__ unsigned f2bf(float f) { unsigned r; asm("v_cvt_pk_bf16_f32 %0, %1, %1" : "=v"(r) : "v"(f)); return r & 0xffffu; }
; __device__ __forceinline__ void gl1_item(PREF p, int l, int item, bool valid, LAS unsigned char* pl, int sw, int lane) {
;     ...
;             for (int ss = 0; ss < 16; ++ss) { const int s = g4 * 16 + ss; const int i = d ? 63 - s : s; const size_t rowi = (size_t)(row0 + i * rstride);
;                 bc += gv[ss];
;                 const float en = __expf(-bc), ep = __expf(bc);
;                 const float kt = kc[ss] * en, qt = qc[ss] * 0.125f * ep;
;                 const unsigned ktb = f2bf(kt);
;                 sKt[lane * 72 + i] = (bf16_t)ktb;
;                 QK[rowi * 1024 + d * 512 + h * 64 + lane] = (bf16_t)f2bf(qt);
;                 QK[rowi * 1024 + d * 512 + 256 + h * 64 + lane] = (bf16_t)ktb;
;             }
	v_exp_f32_e32 v33, v33
	v_lshlrev_b32_e32 v196, 16, v196
	v_lshlrev_b32_e32 v197, 16, v197
	v_lshlrev_b32_e32 v198, 16, v198
	v_lshlrev_b32_e32 v199, 16, v199
	v_lshlrev_b32_e32 v200, 16, v200
	v_lshlrev_b32_e32 v201, 16, v201
	v_lshlrev_b32_e32 v202, 16, v202
	v_lshlrev_b32_e32 v203, 16, v203
	v_lshlrev_b32_e32 v204, 16, v204
	v_lshlrev_b32_e32 v205, 16, v205
	v_lshlrev_b32_e32 v206, 16, v206
	v_lshlrev_b32_e32 v207, 16, v207
	v_lshlrev_b32_e32 v208, 16, v208
	v_lshlrev_b32_e32 v209, 16, v209
	v_lshlrev_b32_e32 v210, 16, v210
	v_lshlrev_b32_e32 v211, 16, v211
	v_lshlrev_b32_e32 v180, 16, v180
	v_lshlrev_b32_e32 v181, 16, v181
	v_lshlrev_b32_e32 v182, 16, v182
	v_lshlrev_b32_e32 v183, 16, v183
	v_lshlrev_b32_e32 v184, 16, v184
	v_lshlrev_b32_e32 v185, 16, v185
	v_lshlrev_b32_e32 v186, 16, v186
	v_lshlrev_b32_e32 v187, 16, v187
	v_lshlrev_b32_e32 v188, 16, v188
	v_lshlrev_b32_e32 v189, 16, v189
	v_lshlrev_b32_e32 v190, 16, v190
	v_lshlrev_b32_e32 v191, 16, v191
	v_lshlrev_b32_e32 v192, 16, v192
	v_lshlrev_b32_e32 v193, 16, v193
	v_lshlrev_b32_e32 v194, 16, v194
	v_lshlrev_b32_e32 v195, 16, v195
	v_mul_f32_e32 v18, v18, v196
	v_mul_f32_e32 v19, v19, v197
	v_mul_f32_e32 v20, v20, v198
	v_mul_f32_e32 v21, v21, v199
	v_mul_f32_e32 v22, v22, v200
	v_mul_f32_e32 v23, v23, v201
	v_mul_f32_e32 v24, v24, v202
	v_mul_f32_e32 v25, v25, v203
	v_mul_f32_e32 v26, v26, v204
	v_mul_f32_e32 v27, v27, v205
	v_mul_f32_e32 v28, v28, v206
	v_mul_f32_e32 v29, v29, v207
	v_mul_f32_e32 v30, v30, v208
	v_mul_f32_e32 v31, v31, v209
	v_mul_f32_e32 v32, v32, v210
	v_mul_f32_e32 v33, v33, v211
	v_mul_f32_e32 v70, 0x3e000000, v180
	v_mul_f32_e32 v71, 0x3e000000, v181
	v_mul_f32_e32 v72, 0x3e000000, v182
	v_mul_f32_e32 v73, 0x3e000000, v183
	v_mul_f32_e32 v74, 0x3e000000, v184
	v_mul_f32_e32 v75, 0x3e000000, v185
	v_mul_f32_e32 v76, 0x3e000000, v186
	v_mul_f32_e32 v77, 0x3e000000, v187
	v_mul_f32_e32 v78, 0x3e000000, v188
	v_mul_f32_e32 v79, 0x3e000000, v189
	v_mul_f32_e32 v80, 0x3e000000, v190
	v_mul_f32_e32 v81, 0x3e000000, v191
	v_mul_f32_e32 v82, 0x3e000000, v192
	v_mul_f32_e32 v83, 0x3e000000, v193
	v_mul_f32_e32 v84, 0x3e000000, v194
	v_mul_f32_e32 v85, 0x3e000000, v195
	v_mul_f32_e32 v244, v70, v244
	v_mul_f32_e32 v245, v71, v245
	v_mul_f32_e32 v246, v72, v246
	v_mul_f32_e32 v247, v73, v247
	v_mul_f32_e32 v114, v74, v114
	v_mul_f32_e32 v115, v75, v115
	v_mul_f32_e32 v116, v76, v116
	v_mul_f32_e32 v117, v77, v117
	v_mul_f32_e32 v248, v78, v248
	v_mul_f32_e32 v249, v79, v249
	v_mul_f32_e32 v250, v80, v250
	v_mul_f32_e32 v251, v81, v251
	v_mul_f32_e32 v118, v82, v118
	v_mul_f32_e32 v119, v83, v119
	v_mul_f32_e32 v120, v84, v120
	v_mul_f32_e32 v121, v85, v121
	v_cvt_pk_bf16_f32 v18, v18, v244
	v_cvt_pk_bf16_f32 v19, v19, v245
	v_cvt_pk_bf16_f32 v20, v20, v246
	v_cvt_pk_bf16_f32 v21, v21, v247
	v_cvt_pk_bf16_f32 v22, v22, v114
	v_cvt_pk_bf16_f32 v23, v23, v115
	v_cvt_pk_bf16_f32 v24, v24, v116
	v_cvt_pk_bf16_f32 v25, v25, v117
	v_cvt_pk_bf16_f32 v26, v26, v248
	v_cvt_pk_bf16_f32 v27, v27, v249
	v_cvt_pk_bf16_f32 v28, v28, v250
	v_cvt_pk_bf16_f32 v29, v29, v251
	v_cvt_pk_bf16_f32 v30, v30, v118
	v_cvt_pk_bf16_f32 v31, v31, v119
	v_cvt_pk_bf16_f32 v32, v32, v120
	v_cvt_pk_bf16_f32 v33, v33, v121
	ds_write_b16 v60, v18
	v_add_u32_e32 v60, v61, v60
	global_store_short_d16_hi v134, v18, s[4:5]
	global_store_short v134, v18, s[4:5] offset:512
	s_add_u32 s4, s4, s56
	s_addc_u32 s5, s5, s3
	ds_write_b16 v60, v19
	v_add_u32_e32 v60, v61, v60
	global_store_short_d16_hi v134, v19, s[4:5]
	global_store_short v134, v19, s[4:5] offset:512
	s_add_u32 s4, s4, s56
	s_addc_u32 s5, s5, s3
	ds_write_b16 v60, v20
	v_add_u32_e32 v60, v61, v60
	global_store_short_d16_hi v134, v20, s[4:5]
	global_store_short v134, v20, s[4:5] offset:512
	s_add_u32 s4, s4, s56
	s_addc_u32 s5, s5, s3
	ds_write_b16 v60, v21
	v_add_u32_e32 v60, v61, v60
	global_store_short_d16_hi v134, v21, s[4:5]
	global_store_short v134, v21, s[4:5] offset:512
	s_add_u32 s4, s4, s56
	s_addc_u32 s5, s5, s3
	ds_write_b16 v60, v22
	v_add_u32_e32 v60, v61, v60
	global_store_short_d16_hi v134, v22, s[4:5]
	global_store_short v134, v22, s[4:5] offset:512
	s_add_u32 s4, s4, s56
	s_addc_u32 s5, s5, s3
	ds_write_b16 v60, v23
	v_add_u32_e32 v60, v61, v60
	global_store_short_d16_hi v134, v23, s[4:5]
	global_store_short v134, v23, s[4:5] offset:512
	s_add_u32 s4, s4, s56
	s_addc_u32 s5, s5, s3
	ds_write_b16 v60, v24
	v_add_u32_e32 v60, v61, v60
	global_store_short_d16_hi v134, v24, s[4:5]
	global_store_short v134, v24, s[4:5] offset:512
	s_add_u32 s4, s4, s56
	s_addc_u32 s5, s5, s3
	ds_write_b16 v60, v25
	v_add_u32_e32 v60, v61, v60
	global_store_short_d16_hi v134, v25, s[4:5]
	global_store_short v134, v25, s[4:5] offset:512
	s_add_u32 s4, s4, s56
	s_addc_u32 s5, s5, s3
	ds_write_b16 v60, v26
	v_add_u32_e32 v60, v61, v60
	global_store_short_d16_hi v134, v26, s[4:5]
	global_store_short v134, v26, s[4:5] offset:512
	s_add_u32 s4, s4, s56
	s_addc_u32 s5, s5, s3
	ds_write_b16 v60, v27
	v_add_u32_e32 v60, v61, v60
	global_store_short_d16_hi v134, v27, s[4:5]
	global_store_short v134, v27, s[4:5] offset:512
	s_add_u32 s4, s4, s56
	s_addc_u32 s5, s5, s3
	ds_write_b16 v60, v28
	v_add_u32_e32 v60, v61, v60
	global_store_short_d16_hi v134, v28, s[4:5]
	global_store_short v134, v28, s[4:5] offset:512
	s_add_u32 s4, s4, s56
	s_addc_u32 s5, s5, s3
	ds_write_b16 v60, v29
	v_add_u32_e32 v60, v61, v60
	global_store_short_d16_hi v134, v29, s[4:5]
	global_store_short v134, v29, s[4:5] offset:512
	s_add_u32 s4, s4, s56
	s_addc_u32 s5, s5, s3
	ds_write_b16 v60, v30
	v_add_u32_e32 v60, v61, v60
	global_store_short_d16_hi v134, v30, s[4:5]
; __device__ __forceinline__ void gl1_item(PREF p, int l, int item, bool valid, LAS unsigned char* pl, int sw, int lane) {
;     ...
;             for (int ss = 0; ss < 16; ++ss) { const int s = g4 * 16 + ss; const int i = d ? 63 - s : s;
;                 float z = bup;
; #pragma unroll
;                 for (int r2 = 0; r2 < 8; ++r2) { const unsigned w = (unsigned)__builtin_amdgcn_readlane((int)lrp[r2], i);
;                     z = __builtin_amdgcn_fdot2_f32_bf16(__builtin_bit_cast(bf16x2_t, w), __builtin_bit_cast(bf16x2_t, wupp[r2]), z, false); }
;                 gv[ss] = -(fmaxf(-z, 0.f) + __logf(1.f + __expf(-fabsf(z)))) * (1.f / 16.f);
;                 __builtin_amdgcn_sched_barrier(0);
;             }
	global_store_short v134, v30, s[4:5] offset:512
	s_add_u32 s4, s4, s56
	s_addc_u32 s5, s5, s3
	ds_write_b16 v60, v31
	v_add_u32_e32 v60, v61, v60
	global_store_short_d16_hi v134, v31, s[4:5]
	global_store_short v134, v31, s[4:5] offset:512
	s_add_u32 s4, s4, s56
	s_addc_u32 s5, s5, s3
	ds_write_b16 v60, v32
	v_add_u32_e32 v60, v61, v60
	global_store_short_d16_hi v134, v32, s[4:5]
	global_store_short v134, v32, s[4:5] offset:512
	s_add_u32 s4, s4, s56
	s_addc_u32 s5, s5, s3
	ds_write_b16 v60, v33
	v_add_u32_e32 v60, v61, v60
	global_store_short_d16_hi v134, v33, s[4:5]
	global_store_short v134, v33, s[4:5] offset:512
	s_add_u32 s4, s4, s56
	s_addc_u32 s5, s5, s3
	v_mov_b32_e32 v236, v16
	v_mov_b32_e32 v106, v124
	v_mov_b32_e32 v237, v16
	v_mov_b32_e32 v107, v124
	v_mov_b32_e32 v238, v16
	v_mov_b32_e32 v108, v124
	v_mov_b32_e32 v239, v16
	v_mov_b32_e32 v109, v124
	v_mov_b32_e32 v240, v16
	v_mov_b32_e32 v110, v124
	v_mov_b32_e32 v241, v16
	v_mov_b32_e32 v111, v124
	v_mov_b32_e32 v242, v16
	v_mov_b32_e32 v112, v124
	v_mov_b32_e32 v243, v16
	v_mov_b32_e32 v113, v124
	v_mov_b32_e32 v244, v16
	v_mov_b32_e32 v114, v124
	v_mov_b32_e32 v245, v16
	v_mov_b32_e32 v115, v124
	v_mov_b32_e32 v246, v16
	v_mov_b32_e32 v116, v124
	v_mov_b32_e32 v247, v16
	v_mov_b32_e32 v117, v124
	v_mov_b32_e32 v248, v16
	v_mov_b32_e32 v118, v124
	v_mov_b32_e32 v249, v16
	v_mov_b32_e32 v119, v124
	v_mov_b32_e32 v250, v16
	v_mov_b32_e32 v120, v124
	v_mov_b32_e32 v251, v16
	v_mov_b32_e32 v121, v124
	s_nop 1
	v_mfma_f32_32x32x16_bf16 v[236:251], v[4:7], v[8:11], v[236:251]
	v_mfma_f32_32x32x16_bf16 v[106:121], v[4:7], v[12:15], v[106:121]
	s_nop 15
	s_nop 15
	v_permlane32_swap_b32 v236, v106
	v_permlane32_swap_b32 v237, v107
	v_permlane32_swap_b32 v238, v108
	v_permlane32_swap_b32 v239, v109
	v_permlane32_swap_b32 v240, v110
	v_permlane32_swap_b32 v241, v111
	v_permlane32_swap_b32 v242, v112
	v_permlane32_swap_b32 v243, v113
	v_permlane32_swap_b32 v244, v114
	v_permlane32_swap_b32 v245, v115
	v_permlane32_swap_b32 v246, v116
	v_permlane32_swap_b32 v247, v117
	v_permlane32_swap_b32 v248, v118
	v_permlane32_swap_b32 v249, v119
	v_permlane32_swap_b32 v250, v120
	v_permlane32_swap_b32 v251, v121
	v_mul_f32_e64 v18, |v236|, s1
	v_mul_f32_e64 v19, |v237|, s1
	v_mul_f32_e64 v20, |v238|, s1
	v_mul_f32_e64 v21, |v239|, s1
	v_mul_f32_e64 v22, |v106|, s1
	v_mul_f32_e64 v23, |v107|, s1
	v_mul_f32_e64 v24, |v108|, s1
	v_mul_f32_e64 v25, |v109|, s1
	v_mul_f32_e64 v26, |v240|, s1
	v_mul_f32_e64 v27, |v241|, s1
	v_mul_f32_e64 v28, |v242|, s1
	v_mul_f32_e64 v29, |v243|, s1
	v_mul_f32_e64 v30, |v110|, s1
	v_mul_f32_e64 v31, |v111|, s1
	v_mul_f32_e64 v32, |v112|, s1
	v_mul_f32_e64 v33, |v113|, s1
	v_exp_f32_e32 v18, v18
	v_exp_f32_e32 v19, v19
	v_exp_f32_e32 v20, v20
	v_exp_f32_e32 v21, v21
	v_exp_f32_e32 v22, v22
	v_exp_f32_e32 v23, v23
	v_exp_f32_e32 v24, v24
	v_exp_f32_e32 v25, v25
	v_exp_f32_e32 v26, v26
	v_exp_f32_e32 v27, v27
	v_exp_f32_e32 v28, v28
	v_exp_f32_e32 v29, v29
	v_exp_f32_e32 v30, v30
	v_exp_f32_e32 v31, v31
	v_exp_f32_e32 v32, v32
	v_exp_f32_e32 v33, v33
	v_max_f32_e64 v236, -v236, 0
	v_max_f32_e64 v237, -v237, 0
	v_max_f32_e64 v238, -v238, 0
	v_max_f32_e64 v239, -v239, 0
	v_max_f32_e64 v106, -v106, 0
	v_max_f32_e64 v107, -v107, 0
	v_max_f32_e64 v108, -v108, 0
	v_max_f32_e64 v109, -v109, 0
	v_max_f32_e64 v240, -v240, 0
	v_max_f32_e64 v241, -v241, 0
	v_max_f32_e64 v242, -v242, 0
	v_max_f32_e64 v243, -v243, 0
	v_max_f32_e64 v110, -v110, 0
	v_max_f32_e64 v111, -v111, 0
	v_max_f32_e64 v112, -v112, 0
	v_max_f32_e64 v113, -v113, 0
	v_add_f32_e32 v18, 1.0, v18
	v_add_f32_e32 v19, 1.0, v19
	v_add_f32_e32 v20, 1.0, v20
	v_add_f32_e32 v21, 1.0, v21
	v_add_f32_e32 v22, 1.0, v22
	v_add_f32_e32 v23, 1.0, v23
	v_add_f32_e32 v24, 1.0, v24
	v_add_f32_e32 v25, 1.0, v25
	v_add_f32_e32 v26, 1.0, v26
	v_add_f32_e32 v27, 1.0, v27
	v_add_f32_e32 v28, 1.0, v28
	v_add_f32_e32 v29, 1.0, v29
	v_add_f32_e32 v30, 1.0, v30
	v_add_f32_e32 v31, 1.0, v31
	v_add_f32_e32 v32, 1.0, v32
	v_add_f32_e32 v33, 1.0, v33
	v_log_f32_e32 v18, v18
	v_log_f32_e32 v19, v19
	v_log_f32_e32 v20, v20
	v_log_f32_e32 v21, v21
	v_log_f32_e32 v22, v22
	v_log_f32_e32 v23, v23
	v_log_f32_e32 v24, v24
	v_log_f32_e32 v25, v25
	v_log_f32_e32 v26, v26
	v_log_f32_e32 v27, v27
	v_log_f32_e32 v28, v28
	v_log_f32_e32 v29, v29
	v_log_f32_e32 v30, v30
	v_log_f32_e32 v31, v31
	v_log_f32_e32 v32, v32
	v_log_f32_e32 v33, v33
	v_fmac_f32_e32 v236, 0x3f317218, v18
	v_fmac_f32_e32 v237, 0x3f317218, v19
	v_fmac_f32_e32 v238, 0x3f317218, v20
	v_fmac_f32_e32 v239, 0x3f317218, v21
	v_fmac_f32_e32 v106, 0x3f317218, v22
	v_fmac_f32_e32 v107, 0x3f317218, v23
	v_fmac_f32_e32 v108, 0x3f317218, v24
	v_fmac_f32_e32 v109, 0x3f317218, v25
	v_fmac_f32_e32 v240, 0x3f317218, v26
	v_fmac_f32_e32 v241, 0x3f317218, v27
	v_fmac_f32_e32 v242, 0x3f317218, v28
	v_fmac_f32_e32 v243, 0x3f317218, v29
	v_fmac_f32_e32 v110, 0x3f317218, v30
	v_fmac_f32_e32 v111, 0x3f317218, v31
	v_fmac_f32_e32 v112, 0x3f317218, v32
	v_fmac_f32_e32 v113, 0x3f317218, v33
	v_fma_f32 v70, v236, s49, v17
	v_fma_f32 v71, v237, s49, v70
	v_fma_f32 v72, v238, s49, v71
	v_fma_f32 v73, v239, s49, v72
	v_fma_f32 v74, v106, s49, v73
	v_fma_f32 v75, v107, s49, v74
	v_fma_f32 v76, v108, s49, v75
	v_fma_f32 v77, v109, s49, v76
	v_fma_f32 v78, v240, s49, v77
	v_fma_f32 v79, v241, s49, v78
	v_fma_f32 v80, v242, s49, v79
	v_fma_f32 v81, v243, s49, v80
	v_fma_f32 v82, v110, s49, v81
	v_fma_f32 v83, v111, s49, v82
	v_fma_f32 v84, v112, s49, v83
	v_fma_f32 v85, v113, s49, v84
	v_mov_b32_e32 v17, v85
	s_waitcnt vmcnt(32)
; __device__ __forceinline__ unsigned f2bf(float f) { unsigned r; asm("v_cvt_pk_bf16_f32 %0, %1, %1" : "=v"(r) : "v"(f)); return r & 0xffffu; }
; __device__ __forceinline__ void gl1_item(PREF p, int l, int item, bool valid, LAS unsigned char* pl, int sw, int lane) {
;     ...
;                 for (int ss = 0; ss < 16; ++ss) { const int s = (g4 + 1) * 16 + ss; const int i = d ? 63 - s : s; const bf16_t* pr = P + (size_t)(row0 + i * rstride) * PW + h * 64 + lane;
;                     qn[ss] = __builtin_bit_cast(float, (unsigned)pr[1024]); kn[ss] = __builtin_bit_cast(float, (unsigned)pr[1280]); }
;                 __builtin_amdgcn_sched_barrier(0);
;             }
;             float gv[16];
; #pragma unroll
;             for (int ss = 0; ss < 16; ++ss) { const int s = g4 * 16 + ss; const int i = d ? 63 - s : s;
;                 float z = bup;
; #pragma unroll
;                 for (int r2 = 0; r2 < 8; ++r2) { const unsigned w = (unsigned)__builtin_amdgcn_readlane((int)lrp[r2], i);
;                     z = __builtin_amdgcn_fdot2_f32_bf16(__builtin_bit_cast(bf16x2_t, w), __builtin_bit_cast(bf16x2_t, wupp[r2]), z, false); }
;                 gv[ss] = -(fmaxf(-z, 0.f) + __logf(1.f + __expf(-fabsf(z)))) * (1.f / 16.f);
;                 __builtin_amdgcn_sched_barrier(0);
;             }
; #pragma unroll
;             for (int ss = 0; ss < 16; ++ss) { const int s = g4 * 16 + ss; const int i = d ? 63 - s : s; const size_t rowi = (size_t)(row0 + i * rstride);
;                 bc += gv[ss];
;                 const float en = __expf(-bc), ep = __expf(bc);
;                 const float kt = kc[ss] * en, qt = qc[ss] * 0.125f * ep;
;                 const unsigned ktb = f2bf(kt);
;                 sKt[lane * 72 + i] = (bf16_t)ktb;
;                 QK[rowi * 1024 + d * 512 + h * 64 + lane] = (bf16_t)f2bf(qt);
;                 QK[rowi * 1024 + d * 512 + 256 + h * 64 + lane] = (bf16_t)ktb;
	global_load_short_d16_hi v180, v134, s[6:7]
	global_load_short_d16_hi v196, v134, s[6:7] offset:512
	s_add_u32 s6, s6, s54
	s_addc_u32 s7, s7, s55
	global_load_short_d16_hi v181, v134, s[6:7]
	global_load_short_d16_hi v197, v134, s[6:7] offset:512
	s_add_u32 s6, s6, s54
	s_addc_u32 s7, s7, s55
	global_load_short_d16_hi v182, v134, s[6:7]
	global_load_short_d16_hi v198, v134, s[6:7] offset:512
	s_add_u32 s6, s6, s54
	s_addc_u32 s7, s7, s55
	global_load_short_d16_hi v183, v134, s[6:7]
	global_load_short_d16_hi v199, v134, s[6:7] offset:512
	s_add_u32 s6, s6, s54
	s_addc_u32 s7, s7, s55
	global_load_short_d16_hi v184, v134, s[6:7]
	global_load_short_d16_hi v200, v134, s[6:7] offset:512
	s_add_u32 s6, s6, s54
	s_addc_u32 s7, s7, s55
	global_load_short_d16_hi v185, v134, s[6:7]
	global_load_short_d16_hi v201, v134, s[6:7] offset:512
	s_add_u32 s6, s6, s54
	s_addc_u32 s7, s7, s55
	global_load_short_d16_hi v186, v134, s[6:7]
	global_load_short_d16_hi v202, v134, s[6:7] offset:512
	s_add_u32 s6, s6, s54
	s_addc_u32 s7, s7, s55
	global_load_short_d16_hi v187, v134, s[6:7]
	global_load_short_d16_hi v203, v134, s[6:7] offset:512
	s_add_u32 s6, s6, s54
	s_addc_u32 s7, s7, s55
	global_load_short_d16_hi v188, v134, s[6:7]
	global_load_short_d16_hi v204, v134, s[6:7] offset:512
	s_add_u32 s6, s6, s54
	s_addc_u32 s7, s7, s55
	global_load_short_d16_hi v189, v134, s[6:7]
	global_load_short_d16_hi v205, v134, s[6:7] offset:512
	s_add_u32 s6, s6, s54
	s_addc_u32 s7, s7, s55
	global_load_short_d16_hi v190, v134, s[6:7]
	global_load_short_d16_hi v206, v134, s[6:7] offset:512
	s_add_u32 s6, s6, s54
	s_addc_u32 s7, s7, s55
	global_load_short_d16_hi v191, v134, s[6:7]
	global_load_short_d16_hi v207, v134, s[6:7] offset:512
	s_add_u32 s6, s6, s54
	s_addc_u32 s7, s7, s55
	global_load_short_d16_hi v192, v134, s[6:7]
	global_load_short_d16_hi v208, v134, s[6:7] offset:512
	s_add_u32 s6, s6, s54
	s_addc_u32 s7, s7, s55
	global_load_short_d16_hi v193, v134, s[6:7]
	global_load_short_d16_hi v209, v134, s[6:7] offset:512
	s_add_u32 s6, s6, s54
	s_addc_u32 s7, s7, s55
	global_load_short_d16_hi v194, v134, s[6:7]
	global_load_short_d16_hi v210, v134, s[6:7] offset:512
	s_add_u32 s6, s6, s54
	s_addc_u32 s7, s7, s55
	global_load_short_d16_hi v195, v134, s[6:7]
	global_load_short_d16_hi v211, v134, s[6:7] offset:512
	s_add_u32 s6, s6, s54
	s_addc_u32 s7, s7, s55
	v_mul_f32_e32 v18, 0xbfb8aa3b, v70
	v_mul_f32_e32 v19, 0xbfb8aa3b, v71
	v_mul_f32_e32 v20, 0xbfb8aa3b, v72
	v_mul_f32_e32 v21, 0xbfb8aa3b, v73
	v_mul_f32_e32 v22, 0xbfb8aa3b, v74
	v_mul_f32_e32 v23, 0xbfb8aa3b, v75
	v_mul_f32_e32 v24, 0xbfb8aa3b, v76
	v_mul_f32_e32 v25, 0xbfb8aa3b, v77
	v_mul_f32_e32 v26, 0xbfb8aa3b, v78
	v_mul_f32_e32 v27, 0xbfb8aa3b, v79
	v_mul_f32_e32 v28, 0xbfb8aa3b, v80
	v_mul_f32_e32 v29, 0xbfb8aa3b, v81
	v_mul_f32_e32 v30, 0xbfb8aa3b, v82
	v_mul_f32_e32 v31, 0xbfb8aa3b, v83
	v_mul_f32_e32 v32, 0xbfb8aa3b, v84
	v_mul_f32_e32 v33, 0xbfb8aa3b, v85
	v_exp_f32_e64 v236, -v18
	v_exp_f32_e64 v237, -v19
	v_exp_f32_e64 v238, -v20
	v_exp_f32_e64 v239, -v21
	v_exp_f32_e64 v106, -v22
	v_exp_f32_e64 v107, -v23
	v_exp_f32_e64 v108, -v24
	v_exp_f32_e64 v109, -v25
	v_exp_f32_e64 v240, -v26
	v_exp_f32_e64 v241, -v27
	v_exp_f32_e64 v242, -v28
	v_exp_f32_e64 v243, -v29
	v_exp_f32_e64 v110, -v30
	v_exp_f32_e64 v111, -v31
	v_exp_f32_e64 v112, -v32
	v_exp_f32_e64 v113, -v33
	v_exp_f32_e32 v18, v18
	v_exp_f32_e32 v19, v19
	v_exp_f32_e32 v20, v20
	v_exp_f32_e32 v21, v21
	v_exp_f32_e32 v22, v22
	v_exp_f32_e32 v23, v23
	v_exp_f32_e32 v24, v24
	v_exp_f32_e32 v25, v25
	v_exp_f32_e32 v26, v26
	v_exp_f32_e32 v27, v27
	v_exp_f32_e32 v28, v28
	v_exp_f32_e32 v29, v29
	v_exp_f32_e32 v30, v30
	v_exp_f32_e32 v31, v31
	v_exp_f32_e32 v32, v32
	v_exp_f32_e32 v33, v33
	v_mul_f32_e32 v18, v18, v164
	v_mul_f32_e32 v19, v19, v165
	v_mul_f32_e32 v20, v20, v166
	v_mul_f32_e32 v21, v21, v167
	v_mul_f32_e32 v22, v22, v168
	v_mul_f32_e32 v23, v23, v169
	v_mul_f32_e32 v24, v24, v170
	v_mul_f32_e32 v25, v25, v171
	v_mul_f32_e32 v26, v26, v172
	v_mul_f32_e32 v27, v27, v173
	v_mul_f32_e32 v28, v28, v174
	v_mul_f32_e32 v29, v29, v175
	v_mul_f32_e32 v30, v30, v176
	v_mul_f32_e32 v31, v31, v177
	v_mul_f32_e32 v32, v32, v178
	v_mul_f32_e32 v33, v33, v179
	v_mul_f32_e32 v70, 0x3e000000, v148
	v_mul_f32_e32 v71, 0x3e000000, v149
	v_mul_f32_e32 v72, 0x3e000000, v150
	v_mul_f32_e32 v73, 0x3e000000, v151
	v_mul_f32_e32 v74, 0x3e000000, v152
	v_mul_f32_e32 v75, 0x3e000000, v153
	v_mul_f32_e32 v76, 0x3e000000, v154
	v_mul_f32_e32 v77, 0x3e000000, v155
	v_mul_f32_e32 v78, 0x3e000000, v156
	v_mul_f32_e32 v79, 0x3e000000, v157
	v_mul_f32_e32 v80, 0x3e000000, v158
	v_mul_f32_e32 v81, 0x3e000000, v159
	v_mul_f32_e32 v82, 0x3e000000, v160
	v_mul_f32_e32 v83, 0x3e000000, v161
	v_mul_f32_e32 v84, 0x3e000000, v162
	v_mul_f32_e32 v85, 0x3e000000, v163
	v_mul_f32_e32 v236, v70, v236
	v_mul_f32_e32 v237, v71, v237
	v_mul_f32_e32 v238, v72, v238
	v_mul_f32_e32 v239, v73, v239
	v_mul_f32_e32 v106, v74, v106
	v_mul_f32_e32 v107, v75, v107
	v_mul_f32_e32 v108, v76, v108
	v_mul_f32_e32 v109, v77, v109
	v_mul_f32_e32 v240, v78, v240
	v_mul_f32_e32 v241, v79, v241
	v_mul_f32_e32 v242, v80, v242
	v_mul_f32_e32 v243, v81, v243
	v_mul_f32_e32 v110, v82, v110
	v_mul_f32_e32 v111, v83, v111
	v_mul_f32_e32 v112, v84, v112
	v_mul_f32_e32 v113, v85, v113
	v_cvt_pk_bf16_f32 v18, v18, v236
	v_cvt_pk_bf16_f32 v19, v19, v237
	v_cvt_pk_bf16_f32 v20, v20, v238
	v_cvt_pk_bf16_f32 v21, v21, v239
	v_cvt_pk_bf16_f32 v22, v22, v106
	v_cvt_pk_bf16_f32 v23, v23, v107
	v_cvt_pk_bf16_f32 v24, v24, v108
	v_cvt_pk_bf16_f32 v25, v25, v109
	v_cvt_pk_bf16_f32 v26, v26, v240
	v_cvt_pk_bf16_f32 v27, v27, v241
; __device__ __forceinline__ unsigned f2bf(float f) { unsigned r; asm("v_cvt_pk_bf16_f32 %0, %1, %1" : "=v"(r) : "v"(f)); return r & 0xffffu; }
; __device__ __forceinline__ void gl1_item(PREF p, int l, int item, bool valid, LAS unsigned char* pl, int sw, int lane) {
;     ...
;             for (int ss = 0; ss < 16; ++ss) { const int s = g4 * 16 + ss; const int i = d ? 63 - s : s;
;                 float z = bup;
; #pragma unroll
;                 for (int r2 = 0; r2 < 8; ++r2) { const unsigned w = (unsigned)__builtin_amdgcn_readlane((int)lrp[r2], i);
;                     z = __builtin_amdgcn_fdot2_f32_bf16(__builtin_bit_cast(bf16x2_t, w), __builtin_bit_cast(bf16x2_t, wupp[r2]), z, false); }
;                 gv[ss] = -(fmaxf(-z, 0.f) + __logf(1.f + __expf(-fabsf(z)))) * (1.f / 16.f);
;                 __builtin_amdgcn_sched_barrier(0);
;             }
; #pragma unroll
;             for (int ss = 0; ss < 16; ++ss) { const int s = g4 * 16 + ss; const int i = d ? 63 - s : s; const size_t rowi = (size_t)(row0 + i * rstride);
;                 bc += gv[ss];
;                 const float en = __expf(-bc), ep = __expf(bc);
;                 const float kt = kc[ss] * en, qt = qc[ss] * 0.125f * ep;
;                 const unsigned ktb = f2bf(kt);
;                 sKt[lane * 72 + i] = (bf16_t)ktb;
;                 QK[rowi * 1024 + d * 512 + h * 64 + lane] = (bf16_t)f2bf(qt);
;                 QK[rowi * 1024 + d * 512 + 256 + h * 64 + lane] = (bf16_t)ktb;
;             }
	v_cvt_pk_bf16_f32 v28, v28, v242
	v_cvt_pk_bf16_f32 v29, v29, v243
	v_cvt_pk_bf16_f32 v30, v30, v110
	v_cvt_pk_bf16_f32 v31, v31, v111
	v_cvt_pk_bf16_f32 v32, v32, v112
	v_cvt_pk_bf16_f32 v33, v33, v113
	ds_write_b16 v60, v18
	v_add_u32_e32 v60, v61, v60
	global_store_short_d16_hi v134, v18, s[4:5]
	global_store_short v134, v18, s[4:5] offset:512
	s_add_u32 s4, s4, s56
	s_addc_u32 s5, s5, s3
	ds_write_b16 v60, v19
	v_add_u32_e32 v60, v61, v60
	global_store_short_d16_hi v134, v19, s[4:5]
	global_store_short v134, v19, s[4:5] offset:512
	s_add_u32 s4, s4, s56
	s_addc_u32 s5, s5, s3
	ds_write_b16 v60, v20
	v_add_u32_e32 v60, v61, v60
	global_store_short_d16_hi v134, v20, s[4:5]
	global_store_short v134, v20, s[4:5] offset:512
	s_add_u32 s4, s4, s56
	s_addc_u32 s5, s5, s3
	ds_write_b16 v60, v21
	v_add_u32_e32 v60, v61, v60
	global_store_short_d16_hi v134, v21, s[4:5]
	global_store_short v134, v21, s[4:5] offset:512
	s_add_u32 s4, s4, s56
	s_addc_u32 s5, s5, s3
	ds_write_b16 v60, v22
	v_add_u32_e32 v60, v61, v60
	global_store_short_d16_hi v134, v22, s[4:5]
	global_store_short v134, v22, s[4:5] offset:512
	s_add_u32 s4, s4, s56
	s_addc_u32 s5, s5, s3
	ds_write_b16 v60, v23
	v_add_u32_e32 v60, v61, v60
	global_store_short_d16_hi v134, v23, s[4:5]
	global_store_short v134, v23, s[4:5] offset:512
	s_add_u32 s4, s4, s56
	s_addc_u32 s5, s5, s3
	ds_write_b16 v60, v24
	v_add_u32_e32 v60, v61, v60
	global_store_short_d16_hi v134, v24, s[4:5]
	global_store_short v134, v24, s[4:5] offset:512
	s_add_u32 s4, s4, s56
	s_addc_u32 s5, s5, s3
	ds_write_b16 v60, v25
	v_add_u32_e32 v60, v61, v60
	global_store_short_d16_hi v134, v25, s[4:5]
	global_store_short v134, v25, s[4:5] offset:512
	s_add_u32 s4, s4, s56
	s_addc_u32 s5, s5, s3
	ds_write_b16 v60, v26
	v_add_u32_e32 v60, v61, v60
	global_store_short_d16_hi v134, v26, s[4:5]
	global_store_short v134, v26, s[4:5] offset:512
	s_add_u32 s4, s4, s56
	s_addc_u32 s5, s5, s3
	ds_write_b16 v60, v27
	v_add_u32_e32 v60, v61, v60
	global_store_short_d16_hi v134, v27, s[4:5]
	global_store_short v134, v27, s[4:5] offset:512
	s_add_u32 s4, s4, s56
	s_addc_u32 s5, s5, s3
	ds_write_b16 v60, v28
	v_add_u32_e32 v60, v61, v60
	global_store_short_d16_hi v134, v28, s[4:5]
	global_store_short v134, v28, s[4:5] offset:512
	s_add_u32 s4, s4, s56
	s_addc_u32 s5, s5, s3
	ds_write_b16 v60, v29
	v_add_u32_e32 v60, v61, v60
	global_store_short_d16_hi v134, v29, s[4:5]
	global_store_short v134, v29, s[4:5] offset:512
	s_add_u32 s4, s4, s56
	s_addc_u32 s5, s5, s3
	ds_write_b16 v60, v30
	v_add_u32_e32 v60, v61, v60
	global_store_short_d16_hi v134, v30, s[4:5]
	global_store_short v134, v30, s[4:5] offset:512
	s_add_u32 s4, s4, s56
	s_addc_u32 s5, s5, s3
	ds_write_b16 v60, v31
	v_add_u32_e32 v60, v61, v60
	global_store_short_d16_hi v134, v31, s[4:5]
	global_store_short v134, v31, s[4:5] offset:512
	s_add_u32 s4, s4, s56
	s_addc_u32 s5, s5, s3
	ds_write_b16 v60, v32
	v_add_u32_e32 v60, v61, v60
	global_store_short_d16_hi v134, v32, s[4:5]
	global_store_short v134, v32, s[4:5] offset:512
	s_add_u32 s4, s4, s56
	s_addc_u32 s5, s5, s3
	ds_write_b16 v60, v33
	v_add_u32_e32 v60, v61, v60
	global_store_short_d16_hi v134, v33, s[4:5]
	global_store_short v134, v33, s[4:5] offset:512
	s_add_u32 s4, s4, s56
	s_addc_u32 s5, s5, s3
	v_mul_f32_e64 v18, |v244|, s1
	v_mul_f32_e64 v19, |v245|, s1
	v_mul_f32_e64 v20, |v246|, s1
	v_mul_f32_e64 v21, |v247|, s1
	v_mul_f32_e64 v22, |v114|, s1
	v_mul_f32_e64 v23, |v115|, s1
	v_mul_f32_e64 v24, |v116|, s1
	v_mul_f32_e64 v25, |v117|, s1
	v_mul_f32_e64 v26, |v248|, s1
	v_mul_f32_e64 v27, |v249|, s1
	v_mul_f32_e64 v28, |v250|, s1
	v_mul_f32_e64 v29, |v251|, s1
	v_mul_f32_e64 v30, |v118|, s1
	v_mul_f32_e64 v31, |v119|, s1
	v_mul_f32_e64 v32, |v120|, s1
	v_mul_f32_e64 v33, |v121|, s1
	v_exp_f32_e32 v18, v18
	v_exp_f32_e32 v19, v19
	v_exp_f32_e32 v20, v20
	v_exp_f32_e32 v21, v21
	v_exp_f32_e32 v22, v22
	v_exp_f32_e32 v23, v23
	v_exp_f32_e32 v24, v24
	v_exp_f32_e32 v25, v25
	v_exp_f32_e32 v26, v26
	v_exp_f32_e32 v27, v27
	v_exp_f32_e32 v28, v28
	v_exp_f32_e32 v29, v29
	v_exp_f32_e32 v30, v30
	v_exp_f32_e32 v31, v31
	v_exp_f32_e32 v32, v32
	v_exp_f32_e32 v33, v33
	v_max_f32_e64 v244, -v244, 0
	v_max_f32_e64 v245, -v245, 0
	v_max_f32_e64 v246, -v246, 0
	v_max_f32_e64 v247, -v247, 0
	v_max_f32_e64 v114, -v114, 0
	v_max_f32_e64 v115, -v115, 0
	v_max_f32_e64 v116, -v116, 0
	v_max_f32_e64 v117, -v117, 0
	v_max_f32_e64 v248, -v248, 0
	v_max_f32_e64 v249, -v249, 0
	v_max_f32_e64 v250, -v250, 0
	v_max_f32_e64 v251, -v251, 0
	v_max_f32_e64 v118, -v118, 0
	v_max_f32_e64 v119, -v119, 0
	v_max_f32_e64 v120, -v120, 0
	v_max_f32_e64 v121, -v121, 0
	v_add_f32_e32 v18, 1.0, v18
	v_add_f32_e32 v19, 1.0, v19
	v_add_f32_e32 v20, 1.0, v20
	v_add_f32_e32 v21, 1.0, v21
	v_add_f32_e32 v22, 1.0, v22
	v_add_f32_e32 v23, 1.0, v23
	v_add_f32_e32 v24, 1.0, v24
	v_add_f32_e32 v25, 1.0, v25
	v_add_f32_e32 v26, 1.0, v26
	v_add_f32_e32 v27, 1.0, v27
	v_add_f32_e32 v28, 1.0, v28
	v_add_f32_e32 v29, 1.0, v29
	v_add_f32_e32 v30, 1.0, v30
	v_add_f32_e32 v31, 1.0, v31
	v_add_f32_e32 v32, 1.0, v32
	v_add_f32_e32 v33, 1.0, v33
	v_log_f32_e32 v18, v18
	v_log_f32_e32 v19, v19
	v_log_f32_e32 v20, v20
	v_log_f32_e32 v21, v21
	v_log_f32_e32 v22, v22
	v_log_f32_e32 v23, v23
	v_log_f32_e32 v24, v24
	v_log_f32_e32 v25, v25
	v_log_f32_e32 v26, v26
	v_log_f32_e32 v27, v27
	v_log_f32_e32 v28, v28
	v_log_f32_e32 v29, v29
	v_log_f32_e32 v30, v30
	v_log_f32_e32 v31, v31
	v_log_f32_e32 v32, v32
	v_log_f32_e32 v33, v33
	v_fmac_f32_e32 v244, 0x3f317218, v18
	v_fmac_f32_e32 v245, 0x3f317218, v19
	v_fmac_f32_e32 v246, 0x3f317218, v20
	v_fmac_f32_e32 v247, 0x3f317218, v21
	v_fmac_f32_e32 v114, 0x3f317218, v22
	v_fmac_f32_e32 v115, 0x3f317218, v23
	v_fmac_f32_e32 v116, 0x3f317218, v24
	v_fmac_f32_e32 v117, 0x3f317218, v25
	v_fmac_f32_e32 v248, 0x3f317218, v26
	v_fmac_f32_e32 v249, 0x3f317218, v27
	v_fmac_f32_e32 v250, 0x3f317218, v28
	v_fmac_f32_e32 v251, 0x3f317218, v29
	v_fmac_f32_e32 v118, 0x3f317218, v30
	v_fmac_f32_e32 v119, 0x3f317218, v31
	v_fmac_f32_e32 v120, 0x3f317218, v32
	v_fmac_f32_e32 v121, 0x3f317218, v33
	v_fma_f32 v70, v244, s49, v17
	v_fma_f32 v71, v245, s49, v70
	v_fma_f32 v72, v246, s49, v71
	v_fma_f32 v73, v247, s49, v72
	v_fma_f32 v74, v114, s49, v73
	v_fma_f32 v75, v115, s49, v74
	v_fma_f32 v76, v116, s49, v75
	v_fma_f32 v77, v117, s49, v76
	v_fma_f32 v78, v248, s49, v77
	v_fma_f32 v79, v249, s49, v78
	v_fma_f32 v80, v250, s49, v79
	v_fma_f32 v81, v251, s49, v80
	v_fma_f32 v82, v118, s49, v81
	v_fma_f32 v83, v119, s49, v82
	v_fma_f32 v84, v120, s49, v83
	v_fma_f32 v85, v121, s49, v84
	v_mov_b32_e32 v17, v85
	s_waitcnt vmcnt(32)
; __device__ __forceinline__ unsigned f2bf(float f) { unsigned r; asm("v_cvt_pk_bf16_f32 %0, %1, %1" : "=v"(r) : "v"(f)); return r & 0xffffu; }
; __device__ __forceinline__ void gl1_item(PREF p, int l, int item, bool valid, LAS unsigned char* pl, int sw, int lane) {
;     ...
;             for (int ss = 0; ss < 16; ++ss) { const int s = g4 * 16 + ss; const int i = d ? 63 - s : s; const size_t rowi = (size_t)(row0 + i * rstride);
;                 bc += gv[ss];
;                 const float en = __expf(-bc), ep = __expf(bc);
;                 const float kt = kc[ss] * en, qt = qc[ss] * 0.125f * ep;
;                 const unsigned ktb = f2bf(kt);
;                 sKt[lane * 72 + i] = (bf16_t)ktb;
;                 QK[rowi * 1024 + d * 512 + h * 64 + lane] = (bf16_t)f2bf(qt);
;                 QK[rowi * 1024 + d * 512 + 256 + h * 64 + lane] = (bf16_t)ktb;
	v_mul_f32_e32 v18, 0xbfb8aa3b, v70
	v_mul_f32_e32 v19, 0xbfb8aa3b, v71
	v_mul_f32_e32 v20, 0xbfb8aa3b, v72
	v_mul_f32_e32 v21, 0xbfb8aa3b, v73
	v_mul_f32_e32 v22, 0xbfb8aa3b, v74
	v_mul_f32_e32 v23, 0xbfb8aa3b, v75
	v_mul_f32_e32 v24, 0xbfb8aa3b, v76
	v_mul_f32_e32 v25, 0xbfb8aa3b, v77
	v_mul_f32_e32 v26, 0xbfb8aa3b, v78
	v_mul_f32_e32 v27, 0xbfb8aa3b, v79
	v_mul_f32_e32 v28, 0xbfb8aa3b, v80
	v_mul_f32_e32 v29, 0xbfb8aa3b, v81
	v_mul_f32_e32 v30, 0xbfb8aa3b, v82
	v_mul_f32_e32 v31, 0xbfb8aa3b, v83
	v_mul_f32_e32 v32, 0xbfb8aa3b, v84
	v_mul_f32_e32 v33, 0xbfb8aa3b, v85
	v_exp_f32_e64 v244, -v18
	v_exp_f32_e64 v245, -v19
	v_exp_f32_e64 v246, -v20
	v_exp_f32_e64 v247, -v21
	v_exp_f32_e64 v114, -v22
	v_exp_f32_e64 v115, -v23
	v_exp_f32_e64 v116, -v24
	v_exp_f32_e64 v117, -v25
	v_exp_f32_e64 v248, -v26
	v_exp_f32_e64 v249, -v27
	v_exp_f32_e64 v250, -v28
	v_exp_f32_e64 v251, -v29
	v_exp_f32_e64 v118, -v30
	v_exp_f32_e64 v119, -v31
	v_exp_f32_e64 v120, -v32
	v_exp_f32_e64 v121, -v33
	v_exp_f32_e32 v18, v18
	v_exp_f32_e32 v19, v19
	v_exp_f32_e32 v20, v20
	v_exp_f32_e32 v21, v21
	v_exp_f32_e32 v22, v22
	v_exp_f32_e32 v23, v23
	v_exp_f32_e32 v24, v24
	v_exp_f32_e32 v25, v25
	v_exp_f32_e32 v26, v26
	v_exp_f32_e32 v27, v27
	v_exp_f32_e32 v28, v28
	v_exp_f32_e32 v29, v29
	v_exp_f32_e32 v30, v30
	v_exp_f32_e32 v31, v31
	v_exp_f32_e32 v32, v32
	v_exp_f32_e32 v33, v33
	v_mul_f32_e32 v18, v18, v196
	v_mul_f32_e32 v19, v19, v197
	v_mul_f32_e32 v20, v20, v198
	v_mul_f32_e32 v21, v21, v199
	v_mul_f32_e32 v22, v22, v200
	v_mul_f32_e32 v23, v23, v201
	v_mul_f32_e32 v24, v24, v202
	v_mul_f32_e32 v25, v25, v203
	v_mul_f32_e32 v26, v26, v204
	v_mul_f32_e32 v27, v27, v205
	v_mul_f32_e32 v28, v28, v206
	v_mul_f32_e32 v29, v29, v207
	v_mul_f32_e32 v30, v30, v208
	v_mul_f32_e32 v31, v31, v209
	v_mul_f32_e32 v32, v32, v210
	v_mul_f32_e32 v33, v33, v211
	v_mul_f32_e32 v70, 0x3e000000, v180
	v_mul_f32_e32 v71, 0x3e000000, v181
	v_mul_f32_e32 v72, 0x3e000000, v182
	v_mul_f32_e32 v73, 0x3e000000, v183
	v_mul_f32_e32 v74, 0x3e000000, v184
	v_mul_f32_e32 v75, 0x3e000000, v185
	v_mul_f32_e32 v76, 0x3e000000, v186
	v_mul_f32_e32 v77, 0x3e000000, v187
	v_mul_f32_e32 v78, 0x3e000000, v188
	v_mul_f32_e32 v79, 0x3e000000, v189
	v_mul_f32_e32 v80, 0x3e000000, v190
	v_mul_f32_e32 v81, 0x3e000000, v191
	v_mul_f32_e32 v82, 0x3e000000, v192
	v_mul_f32_e32 v83, 0x3e000000, v193
	v_mul_f32_e32 v84, 0x3e000000, v194
	v_mul_f32_e32 v85, 0x3e000000, v195
	v_mul_f32_e32 v244, v70, v244
	v_mul_f32_e32 v245, v71, v245
	v_mul_f32_e32 v246, v72, v246
	v_mul_f32_e32 v247, v73, v247
	v_mul_f32_e32 v114, v74, v114
	v_mul_f32_e32 v115, v75, v115
	v_mul_f32_e32 v116, v76, v116
	v_mul_f32_e32 v117, v77, v117
	v_mul_f32_e32 v248, v78, v248
	v_mul_f32_e32 v249, v79, v249
	v_mul_f32_e32 v250, v80, v250
	v_mul_f32_e32 v251, v81, v251
	v_mul_f32_e32 v118, v82, v118
	v_mul_f32_e32 v119, v83, v119
	v_mul_f32_e32 v120, v84, v120
	v_mul_f32_e32 v121, v85, v121
	v_cvt_pk_bf16_f32 v18, v18, v244
	v_cvt_pk_bf16_f32 v19, v19, v245
	v_cvt_pk_bf16_f32 v20, v20, v246
	v_cvt_pk_bf16_f32 v21, v21, v247
	v_cvt_pk_bf16_f32 v22, v22, v114
	v_cvt_pk_bf16_f32 v23, v23, v115
	v_cvt_pk_bf16_f32 v24, v24, v116
	v_cvt_pk_bf16_f32 v25, v25, v117
	v_cvt_pk_bf16_f32 v26, v26, v248
	v_cvt_pk_bf16_f32 v27, v27, v249
	v_cvt_pk_bf16_f32 v28, v28, v250
	v_cvt_pk_bf16_f32 v29, v29, v251
	v_cvt_pk_bf16_f32 v30, v30, v118
	v_cvt_pk_bf16_f32 v31, v31, v119
	v_cvt_pk_bf16_f32 v32, v32, v120
	v_cvt_pk_bf16_f32 v33, v33, v121
	ds_write_b16 v60, v18
	v_add_u32_e32 v60, v61, v60
	global_store_short_d16_hi v134, v18, s[4:5]
; __device__ __forceinline__ unsigned f2bf(float f) { unsigned r; asm("v_cvt_pk_bf16_f32 %0, %1, %1" : "=v"(r) : "v"(f)); return r & 0xffffu; }
; __device__ __forceinline__ void gl1_item(PREF p, int l, int item, bool valid, LAS unsigned char* pl, int sw, int lane) {
;     ...
;             for (int ss = 0; ss < 16; ++ss) { const int s = g4 * 16 + ss; const int i = d ? 63 - s : s; const size_t rowi = (size_t)(row0 + i * rstride);
;                 bc += gv[ss];
;                 const float en = __expf(-bc), ep = __expf(bc);
;                 const float kt = kc[ss] * en, qt = qc[ss] * 0.125f * ep;
;                 const unsigned ktb = f2bf(kt);
;                 sKt[lane * 72 + i] = (bf16_t)ktb;
;                 QK[rowi * 1024 + d * 512 + h * 64 + lane] = (bf16_t)f2bf(qt);
;                 QK[rowi * 1024 + d * 512 + 256 + h * 64 + lane] = (bf16_t)ktb;
;             }
; #pragma unroll
;             for (int ss = 0; ss < 16; ++ss) { qc[ss] = bf2f(__builtin_bit_cast(unsigned, qn[ss])); kc[ss] = bf2f(__builtin_bit_cast(unsigned, kn[ss])); }
;         }
;         const float Dv = __expf(bc);
;         sD[lane] = Dv; GLD[(size_t)(seq * NCH + cj) * 64 + lane] = Dv;
	global_store_short v134, v18, s[4:5] offset:512
	s_add_u32 s4, s4, s56
	s_addc_u32 s5, s5, s3
	ds_write_b16 v60, v19
	v_add_u32_e32 v60, v61, v60
	global_store_short_d16_hi v134, v19, s[4:5]
	global_store_short v134, v19, s[4:5] offset:512
	s_add_u32 s4, s4, s56
	s_addc_u32 s5, s5, s3
	ds_write_b16 v60, v20
	v_add_u32_e32 v60, v61, v60
	global_store_short_d16_hi v134, v20, s[4:5]
	global_store_short v134, v20, s[4:5] offset:512
	s_add_u32 s4, s4, s56
	s_addc_u32 s5, s5, s3
	ds_write_b16 v60, v21
	v_add_u32_e32 v60, v61, v60
	global_store_short_d16_hi v134, v21, s[4:5]
	global_store_short v134, v21, s[4:5] offset:512
	s_add_u32 s4, s4, s56
	s_addc_u32 s5, s5, s3
	ds_write_b16 v60, v22
	v_add_u32_e32 v60, v61, v60
	global_store_short_d16_hi v134, v22, s[4:5]
	global_store_short v134, v22, s[4:5] offset:512
	s_add_u32 s4, s4, s56
	s_addc_u32 s5, s5, s3
	ds_write_b16 v60, v23
	v_add_u32_e32 v60, v61, v60
	global_store_short_d16_hi v134, v23, s[4:5]
	global_store_short v134, v23, s[4:5] offset:512
	s_add_u32 s4, s4, s56
	s_addc_u32 s5, s5, s3
	ds_write_b16 v60, v24
	v_add_u32_e32 v60, v61, v60
	global_store_short_d16_hi v134, v24, s[4:5]
	global_store_short v134, v24, s[4:5] offset:512
	s_add_u32 s4, s4, s56
	s_addc_u32 s5, s5, s3
	ds_write_b16 v60, v25
	v_add_u32_e32 v60, v61, v60
	global_store_short_d16_hi v134, v25, s[4:5]
	global_store_short v134, v25, s[4:5] offset:512
	s_add_u32 s4, s4, s56
	s_addc_u32 s5, s5, s3
	ds_write_b16 v60, v26
	v_add_u32_e32 v60, v61, v60
	global_store_short_d16_hi v134, v26, s[4:5]
	global_store_short v134, v26, s[4:5] offset:512
	s_add_u32 s4, s4, s56
	s_addc_u32 s5, s5, s3
	ds_write_b16 v60, v27
	v_add_u32_e32 v60, v61, v60
	global_store_short_d16_hi v134, v27, s[4:5]
	global_store_short v134, v27, s[4:5] offset:512
	s_add_u32 s4, s4, s56
	s_addc_u32 s5, s5, s3
	ds_write_b16 v60, v28
	v_add_u32_e32 v60, v61, v60
	global_store_short_d16_hi v134, v28, s[4:5]
	global_store_short v134, v28, s[4:5] offset:512
	s_add_u32 s4, s4, s56
	s_addc_u32 s5, s5, s3
	ds_write_b16 v60, v29
	v_add_u32_e32 v60, v61, v60
	global_store_short_d16_hi v134, v29, s[4:5]
	global_store_short v134, v29, s[4:5] offset:512
	s_add_u32 s4, s4, s56
	s_addc_u32 s5, s5, s3
	ds_write_b16 v60, v30
	v_add_u32_e32 v60, v61, v60
	global_store_short_d16_hi v134, v30, s[4:5]
	global_store_short v134, v30, s[4:5] offset:512
	s_add_u32 s4, s4, s56
	s_addc_u32 s5, s5, s3
	ds_write_b16 v60, v31
	v_add_u32_e32 v60, v61, v60
	global_store_short_d16_hi v134, v31, s[4:5]
	global_store_short v134, v31, s[4:5] offset:512
	s_add_u32 s4, s4, s56
	s_addc_u32 s5, s5, s3
	ds_write_b16 v60, v32
	v_add_u32_e32 v60, v61, v60
	global_store_short_d16_hi v134, v32, s[4:5]
	global_store_short v134, v32, s[4:5] offset:512
	s_add_u32 s4, s4, s56
	s_addc_u32 s5, s5, s3
	ds_write_b16 v60, v33
	v_add_u32_e32 v60, v61, v60
	global_store_short_d16_hi v134, v33, s[4:5]
	global_store_short v134, v33, s[4:5] offset:512
	s_add_u32 s4, s4, s56
	s_addc_u32 s5, s5, s3
	v_mul_f32_e32 v18, 0x3fb8aa3b, v17
	v_exp_f32_e32 v18, v18
	v_readlane_b32 s50, v253, 55
	v_readlane_b32 s51, v253, 56
	v_readlane_b32 s45, v254, 11
	s_nop 3
	s_load_dwordx2 s[46:47], s[50:51], 0xc0
	s_and_b32 s48, s38, 1
	s_lshr_b32 s45, s45, 7
	s_mul_i32 s45, s45, 0x9200
	s_lshl_b32 s48, s48, 8
	s_add_i32 s45, s45, s48
	v_lshl_add_u32 v86, v64, 2, s45
	ds_write_b32 v86, v18 offset:36864
	s_or_b32 s45, s42, s38
	s_mulk_i32 s45, 0x104
	s_add_i32 s45, s45, s41
	s_lshl_b32 s45, s45, 8
	s_waitcnt lgkmcnt(0)
	s_add_u32 s46, s46, 0xd00000
	s_addc_u32 s47, s47, 0
	s_add_u32 s46, s46, s45
	s_addc_u32 s47, s47, 0
	global_store_dword v135, v18, s[46:47]
